# relabel workgroup index by actual XCC id + arrival rank; GRID_BAR(3,4,5) become group-local (32 workgroups of one XCC, no L2 writeback)
# speedup vs baseline: 1.0080x; 1.0080x over previous
; #define LAS __attribute__((address_space(3)))
; __global__ void __launch_bounds__(NWAVES * 64, 2) hybrid_fwd(Args args) {
;     extern __shared__ __attribute__((aligned(16))) unsigned char lds[];
;     cg::grid_group grid = cg::this_grid();
;     const int tid = threadIdx.x, lane = tid & 63, wave = __builtin_amdgcn_readfirstlane(tid >> 6);
;     const int G = gridDim.x, bx = blockIdx.x, vcu = (G % 8 == 0) ? (bx % 8) * (G / 8) + bx / 8 : bx;
;     const float* x = args.in[0]; const float* norm_mix_w = args.in[1]; const float* w_in = args.in[2]; const float* w_out = args.in[3]; const float* norm_ffn_w = args.in[4];
;     const float* w_gate = args.in[5]; const float* w_up = args.in[6]; const float* w_down = args.in[7]; const float* norm_final_w = args.in[8];
;     float* out = args.out; unsigned char* ws = args.ws;
;     float* SS1 = (float*)(ws + WS_SS); float* SS2 = SS1 + M;
;     bf16* Win_t = (bf16*)(ws + WS_WIN); bf16* Wout_t = (bf16*)(ws + WS_WOUT); bf16* Wgu_t = (bf16*)(ws + WS_WGU); bf16* Wdn_t = (bf16*)(ws + WS_WDN);
;     bf16* HB = (bf16*)(ws + WS_H); bf16* PROJ = (bf16*)(ws + WS_PROJ); bf16* ACT = (bf16*)(ws + WS_PROJ); bf16* MIXED = (bf16*)(ws + WS_MIXED);
;     const int lo = args.ph_lo, hi = args.ph_hi;
;     ...
;     volatile LAS unsigned* MISC = (volatile LAS unsigned*)((LAS unsigned char*)lds + LDS_BYTES - 64);
;     if (tid < 16) MISC[tid] = 0u;
;     __syncthreads();
;     XcdBarrier bar = xcd_barrier_post((unsigned*)(ws + WS_BAR), MISC);
_Z10hybrid_fwd4Args:
	s_load_dwordx2 s[76:77], s[0:1], 0x50
	s_mov_b32 s101, 0
	s_load_dwordx4 s[4:7], s[0:1], 0x40
	v_and_b32_e32 v185, 0x3ff, v0
	s_waitcnt lgkmcnt(0)
	s_load_dword s101, s[0:1], 0x60
	s_getreg_b32 s100, hwreg(HW_REG_XCC_ID, 0, 4)
	s_and_b32 s100, s100, 15
	v_cmp_eq_u32_e32 vcc, 0, v185
	s_and_saveexec_b64 s[98:99], vcc
	s_cbranch_execz .Lvb_posted
	v_mov_b32_e32 v254, s100
	v_lshlrev_b32_e32 v254, 8, v254
	v_add_u32_e32 v254, 0x2f000, v254
	v_mov_b32_e32 v255, 1
	global_atomic_add v253, v254, v255, s[76:77] sc0
	v_mov_b32_e32 v254, 0x20f80
	s_waitcnt vmcnt(0)
	ds_write_b32 v254, v253
	s_waitcnt lgkmcnt(0)
.Lvb_posted:
	s_or_b64 exec, exec, s[98:99]
	s_barrier
	v_mov_b32_e32 v254, 0x20f80
	ds_read_b32 v253, v254
	s_waitcnt lgkmcnt(0)
	v_readfirstlane_b32 s98, v253
	s_cmp_eq_u32 s101, 0x100
	s_cbranch_scc0 .Lvb_keep
	s_cmp_lt_u32 s98, 32
	s_cbranch_scc0 .Lvb_keep
	s_cmp_lt_u32 s100, 8
	s_cbranch_scc0 .Lvb_keep
	s_lshl_b32 s98, s98, 3
	s_or_b32 s2, s98, s100
	s_mov_b32 s99, 0
	s_branch .Lvb_done
.Lvb_keep:
	s_mov_b32 s99, 1
.Lvb_done:
	s_mov_b32 s101, 0
	v_writelane_b32 v244, s4, 0
	s_nop 1
	v_writelane_b32 v244, s5, 1
	v_writelane_b32 v244, s6, 2
	v_writelane_b32 v244, s7, 3
	s_load_dwordx2 s[6:7], s[0:1], 0x60
	s_add_u32 s4, s0, 0x60
	s_addc_u32 s5, s1, 0
	v_readfirstlane_b32 s12, v185
	s_waitcnt lgkmcnt(0)
	v_writelane_b32 v244, s6, 4
	s_and_b32 s3, s6, 7
	s_cmp_lg_u32 s3, 0
	s_mov_b32 s3, s2
	v_writelane_b32 v244, s7, 5
	s_cbranch_scc1 .LBB0_2
	s_load_dwordx2 s[6:7], s[0:1], 0x60
	s_waitcnt lgkmcnt(0)
	s_ashr_i32 s3, s6, 3
	s_ashr_i32 s6, s2, 31
	s_lshr_b32 s6, s6, 29
	s_add_i32 s6, s2, s6
	s_and_b32 s7, s6, -8
	s_sub_i32 s7, s2, s7
	s_mul_i32 s3, s3, s7
	s_ashr_i32 s6, s6, 3
	s_add_i32 s3, s3, s6

; __global__ void __launch_bounds__(NWAVES * 64, 2) hybrid_fwd(Args args) {
;     ...
;     if (tid < 16) MISC[tid] = 0u;
;     __syncthreads();
;     XcdBarrier bar = xcd_barrier_post((unsigned*)(ws + WS_BAR), MISC);
.LBB0_7:
	s_or_b64 exec, exec, s[6:7]
	s_cmp_eq_u32 s99, 1
	s_mov_b32 s99, 0
	s_cbranch_scc0 .Lgb_post_done
	s_mov_b64 exec, s[96:97]
	s_cbranch_execz .Lgb_post_skip
	v_mov_b32_e32 v254, 0x2d000
	v_mov_b32_e32 v255, 1
	global_atomic_add v254, v255, s[76:77]

; #define LAS __attribute__((address_space(3)))
; __global__ void __launch_bounds__(NWAVES * 64, 2) hybrid_fwd(Args args) {
;     ...
;     cg::grid_group grid = cg::this_grid();
;     const int tid = threadIdx.x, lane = tid & 63, wave = __builtin_amdgcn_readfirstlane(tid >> 6);
;     const int G = gridDim.x, bx = blockIdx.x, vcu = (G % 8 == 0) ? (bx % 8) * (G / 8) + bx / 8 : bx;
;     const float* x = args.in[0]; const float* norm_mix_w = args.in[1]; const float* w_in = args.in[2]; const float* w_out = args.in[3]; const float* norm_ffn_w = args.in[4];
;     const float* w_gate = args.in[5]; const float* w_up = args.in[6]; const float* w_down = args.in[7]; const float* norm_final_w = args.in[8];
;     float* out = args.out; unsigned char* ws = args.ws;
;     float* SS1 = (float*)(ws + WS_SS); float* SS2 = SS1 + M;
;     bf16* Win_t = (bf16*)(ws + WS_WIN); bf16* Wout_t = (bf16*)(ws + WS_WOUT); bf16* Wgu_t = (bf16*)(ws + WS_WGU); bf16* Wdn_t = (bf16*)(ws + WS_WDN);
;     bf16* HB = (bf16*)(ws + WS_H); bf16* PROJ = (bf16*)(ws + WS_PROJ); bf16* ACT = (bf16*)(ws + WS_PROJ); bf16* MIXED = (bf16*)(ws + WS_MIXED);
;     const int lo = args.ph_lo, hi = args.ph_hi;
;     ...
;     volatile LAS unsigned* MISC = (volatile LAS unsigned*)((LAS unsigned char*)lds + LDS_BYTES - 64);
;     if (tid < 16) MISC[tid] = 0u;
;     __syncthreads();
;     XcdBarrier bar = xcd_barrier_post((unsigned*)(ws + WS_BAR), MISC);
;     if (hi > 1000) grid.sync();
.Lgb_post_done:
	s_load_dwordx16 s[16:31], s[0:1], 0x0
	v_writelane_b32 v244, s14, 10
	s_cmpk_lt_i32 s15, 0x3e9
	s_nop 0
	v_writelane_b32 v244, s15, 11
	s_cbranch_scc1 .LBB0_19
	v_lshrrev_b32_e32 v1, 20, v0
	v_lshrrev_b32_e32 v0, 10, v0
	v_or_b32_e32 v0, v0, v1
	s_movk_i32 s0, 0x3ff
	v_and_or_b32 v0, v0, s0, v185
	v_cmp_eq_u32_e32 vcc, 0, v0
	s_waitcnt lgkmcnt(0)
	s_barrier
	s_and_saveexec_b64 s[0:1], vcc
	s_cbranch_execz .LBB0_18
	buffer_wbl2 sc1
	s_waitcnt vmcnt(0)
	s_load_dwordx2 s[4:5], s[4:5], 0x58
	v_mov_b32_e32 v2, 0
	s_mov_b64 s[6:7], exec
	v_mbcnt_lo_u32_b32 v1, s6, 0
	v_mbcnt_hi_u32_b32 v1, s7, v1
	s_waitcnt lgkmcnt(0)
	global_load_dword v0, v2, s[4:5] offset:40
	v_cmp_eq_u32_e32 vcc, 0, v1
	s_and_saveexec_b64 s[8:9], vcc
	s_cbranch_execz .LBB0_11
	s_bcnt1_i32_b64 s6, s[6:7]
	v_mov_b32_e32 v3, s6
	global_atomic_add v3, v2, v3, s[4:5] offset:32 sc0

; #define PG8_STAGE(bufoff, gbase, voff) do { _Pragma("unroll") for (int _i = 0; _i < 2; ++_i) \
;         __builtin_amdgcn_global_load_lds((const unsigned*)((const char*)(gbase) + (voff)[_i]), (PG8_LAS unsigned*)(lds + (bufoff) + ldsw + _i * 8192), 16, 0, 0); } while (0)
; #define PG8_LDA(dst, b, h) do { _Pragma("unroll") for (int m = 0; m < 4; ++m) _Pragma("unroll") for (int k = 0; k < 2; ++k) dst[m][k] = *(const PG8_LAS bf16x8*)(lds + PG8_SA(b, h) + aoff + m * 2048 + k * 1024); } while (0)
; #define PG8_LDB(dst, b, h) do { _Pragma("unroll") for (int n = 0; n < 2; ++n) _Pragma("unroll") for (int k = 0; k < 2; ++k) dst[n][k] = *(const PG8_LAS bf16x8*)(lds + PG8_SB(b, h) + boff + n * 2048 + k * 1024); } while (0)
; #define PG8_MMA(ai, bj, At, Bt) do { __builtin_amdgcn_s_setprio(1); _Pragma("unroll") for (int m = 0; m < 4; ++m) _Pragma("unroll") for (int n = 0; n < 2; ++n) _Pragma("unroll") for (int k = 0; k < 2; ++k) \
;         acc[ai][bj][m][n] = __builtin_amdgcn_mfma_f32_16x16x32_bf16(Bt[n][k], At[m][k], acc[ai][bj][m][n], 0, 0, 0); __builtin_amdgcn_s_setprio(0); } while (0)
; #define PG8_WAIT_V(n) asm volatile("s_waitcnt vmcnt(" #n ")" ::: "memory")
; template <class Epi, class Sched, bool ALIGN_EPI = false, bool SP2 = false>
; __device__ __forceinline__ void gemm_phase(PG8_LAS unsigned char* lds, const Gemm g, const Sched& S, const Epi& E) {
;     ...
;             PG8_LDB(B0, 0, 0); PG8_LDB(B1, 0, 1); PG8_SCHED; PG8_LDA(At, 0, 0); PG8_STAGE(PG8_SA(1, 1), a1 + hstep, voffA);
;             PG8_WAIT_V(8); PG8_WAIT_L(0); PG8_BAR; PG8_MMA(0, 0, At, B0); PG8_MMA(0, 1, At, B1); PG8_BAR; PG8_SCHED;
;             PG8_LDA(At, 0, 1); PG8_STAGE(PG8_SB(0, 0), b2, voffB); PG8_STAGE(PG8_SB(0, 1), b2 + hstep, voffB); PG8_STAGE(PG8_SA(0, 0), a2, voffA);
;             PG8_WAIT_V(8); PG8_WAIT_L(0); PG8_BAR; PG8_MMA(1, 0, At, B0); PG8_MMA(1, 1, At, B1); PG8_BAR; PG8_SCHED;
;             PG8_LDB(B0, 1, 0); PG8_LDB(B1, 1, 1); PG8_SCHED; PG8_LDA(At, 1, 0); PG8_STAGE(PG8_SA(0, 1), a2 + hstep, voffA);
;             PG8_WAIT_V(8); PG8_WAIT_L(0); PG8_BAR; PG8_MMA(0, 0, At, B0); PG8_MMA(0, 1, At, B1); PG8_BAR; PG8_SCHED;
;             PG8_LDA(At, 1, 1); PG8_STAGE(PG8_SB(1, 0), b3, voffB); PG8_STAGE(PG8_SB(1, 1), b3 + hstep, voffB); PG8_STAGE(PG8_SA(1, 0), a3, voffA);
;             PG8_WAIT_V(8); PG8_WAIT_L(0); PG8_BAR; PG8_MMA(1, 0, At, B0); PG8_MMA(1, 1, At, B1); PG8_BAR; PG8_SCHED;
.Lp1_kloop0:
	s_waitcnt vmcnt(8)
	s_waitcnt lgkmcnt(0)
	s_barrier
	v_mfma_f32_16x16x32_bf16 v[0:3], v[196:199], v[128:131], v[0:3]
	ds_read_b128 v[212:215], v247 offset:16384
	v_mfma_f32_16x16x32_bf16 v[0:3], v[200:203], v[132:135], v[0:3]
	ds_read_b128 v[216:219], v248 offset:16384
	v_mfma_f32_16x16x32_bf16 v[4:7], v[208:211], v[132:135], v[4:7]
	ds_read_b128 v[220:223], v247 offset:18432
	v_mfma_f32_16x16x32_bf16 v[4:7], v[204:207], v[128:131], v[4:7]
	ds_read_b128 v[224:227], v248 offset:18432
	v_mfma_f32_16x16x32_bf16 v[12:15], v[204:207], v[136:139], v[12:15]
	s_add_i32 m0, s35, 0x0
	v_mfma_f32_16x16x32_bf16 v[12:15], v[208:211], v[140:143], v[12:15]
	global_load_lds_dwordx4 v249, s[30:31]
	v_mfma_f32_16x16x32_bf16 v[8:11], v[200:203], v[140:143], v[8:11]
	s_add_i32 m0, s35, 0x2000
	v_mfma_f32_16x16x32_bf16 v[8:11], v[196:199], v[136:139], v[8:11]
	global_load_lds_dwordx4 v250, s[30:31]
	v_mfma_f32_16x16x32_bf16 v[16:19], v[196:199], v[144:147], v[16:19]
	s_add_i32 m0, s35, 0x10000
	v_mfma_f32_16x16x32_bf16 v[16:19], v[200:203], v[148:151], v[16:19]
	global_load_lds_dwordx4 v251, s[32:33]
	v_mfma_f32_16x16x32_bf16 v[20:23], v[208:211], v[148:151], v[20:23]
	s_add_i32 m0, s35, 0x12000
	v_mfma_f32_16x16x32_bf16 v[20:23], v[204:207], v[144:147], v[20:23]
	global_load_lds_dwordx4 v252, s[32:33]
	v_mfma_f32_16x16x32_bf16 v[28:31], v[204:207], v[152:155], v[28:31]
	ds_read_b128 v[160:163], v245 offset:16384
	v_mfma_f32_16x16x32_bf16 v[28:31], v[208:211], v[156:159], v[28:31]
	ds_read_b128 v[164:167], v246 offset:16384
	v_mfma_f32_16x16x32_bf16 v[24:27], v[200:203], v[156:159], v[24:27]
	ds_read_b128 v[168:171], v245 offset:18432
	v_mfma_f32_16x16x32_bf16 v[24:27], v[196:199], v[152:155], v[24:27]
	ds_read_b128 v[172:175], v246 offset:18432
	s_waitcnt lgkmcnt(4)
	v_mfma_f32_16x16x32_bf16 v[32:35], v[212:215], v[128:131], v[32:35]
	ds_read_b128 v[176:179], v245 offset:20480
	v_mfma_f32_16x16x32_bf16 v[32:35], v[216:219], v[132:135], v[32:35]
	ds_read_b128 v[180:183], v246 offset:20480
	v_mfma_f32_16x16x32_bf16 v[36:39], v[224:227], v[132:135], v[36:39]
	ds_read_b128 v[188:191], v245 offset:22528
	v_mfma_f32_16x16x32_bf16 v[36:39], v[220:223], v[128:131], v[36:39]
	ds_read_b128 v[192:195], v246 offset:22528
	v_mfma_f32_16x16x32_bf16 v[44:47], v[220:223], v[136:139], v[44:47]
	v_mfma_f32_16x16x32_bf16 v[44:47], v[224:227], v[140:143], v[44:47]
	v_mfma_f32_16x16x32_bf16 v[40:43], v[216:219], v[140:143], v[40:43]
	v_mfma_f32_16x16x32_bf16 v[40:43], v[212:215], v[136:139], v[40:43]
	v_mfma_f32_16x16x32_bf16 v[48:51], v[212:215], v[144:147], v[48:51]
	v_mfma_f32_16x16x32_bf16 v[48:51], v[216:219], v[148:151], v[48:51]
	v_mfma_f32_16x16x32_bf16 v[52:55], v[224:227], v[148:151], v[52:55]
	v_mfma_f32_16x16x32_bf16 v[52:55], v[220:223], v[144:147], v[52:55]
	v_mfma_f32_16x16x32_bf16 v[60:63], v[220:223], v[152:155], v[60:63]
	v_mfma_f32_16x16x32_bf16 v[60:63], v[224:227], v[156:159], v[60:63]
	v_mfma_f32_16x16x32_bf16 v[56:59], v[216:219], v[156:159], v[56:59]
	v_mfma_f32_16x16x32_bf16 v[56:59], v[212:215], v[152:155], v[56:59]
	s_waitcnt vmcnt(8)
	s_waitcnt lgkmcnt(0)
	s_barrier
	v_mfma_f32_16x16x32_bf16 v[96:99], v[212:215], v[160:163], v[96:99]
	s_add_i32 m0, s35, 0x4000
	v_mfma_f32_16x16x32_bf16 v[96:99], v[216:219], v[164:167], v[96:99]
	global_load_lds_dwordx4 v249, s[56:57]
	v_mfma_f32_16x16x32_bf16 v[100:103], v[224:227], v[164:167], v[100:103]
	s_add_i32 m0, s35, 0x6000
	v_mfma_f32_16x16x32_bf16 v[100:103], v[220:223], v[160:163], v[100:103]
	global_load_lds_dwordx4 v250, s[56:57]
	v_mfma_f32_16x16x32_bf16 v[108:111], v[220:223], v[168:171], v[108:111]
	s_add_i32 m0, s35, 0x14000
	v_mfma_f32_16x16x32_bf16 v[108:111], v[224:227], v[172:175], v[108:111]
	global_load_lds_dwordx4 v251, s[58:59]
	v_mfma_f32_16x16x32_bf16 v[104:107], v[216:219], v[172:175], v[104:107]
	s_add_i32 m0, s35, 0x16000
	v_mfma_f32_16x16x32_bf16 v[104:107], v[212:215], v[168:171], v[104:107]
	global_load_lds_dwordx4 v252, s[58:59]
	v_mfma_f32_16x16x32_bf16 v[112:115], v[212:215], v[176:179], v[112:115]
	ds_read_b128 v[128:131], v245 offset:32768
	v_mfma_f32_16x16x32_bf16 v[112:115], v[216:219], v[180:183], v[112:115]
	ds_read_b128 v[132:135], v246 offset:32768
	v_mfma_f32_16x16x32_bf16 v[116:119], v[224:227], v[180:183], v[116:119]
	ds_read_b128 v[136:139], v245 offset:34816
	v_mfma_f32_16x16x32_bf16 v[116:119], v[220:223], v[176:179], v[116:119]
	ds_read_b128 v[140:143], v246 offset:34816
	v_mfma_f32_16x16x32_bf16 v[124:127], v[220:223], v[188:191], v[124:127]
	ds_read_b128 v[144:147], v245 offset:36864
	v_mfma_f32_16x16x32_bf16 v[124:127], v[224:227], v[192:195], v[124:127]
	ds_read_b128 v[148:151], v246 offset:36864
	v_mfma_f32_16x16x32_bf16 v[120:123], v[216:219], v[192:195], v[120:123]
	ds_read_b128 v[152:155], v245 offset:38912
	v_mfma_f32_16x16x32_bf16 v[120:123], v[212:215], v[188:191], v[120:123]
	ds_read_b128 v[156:159], v246 offset:38912
	v_mfma_f32_16x16x32_bf16 v[64:67], v[196:199], v[160:163], v[64:67]
	ds_read_b128 v[212:215], v247 offset:49152
	v_mfma_f32_16x16x32_bf16 v[64:67], v[200:203], v[164:167], v[64:67]
	ds_read_b128 v[216:219], v248 offset:49152
	v_mfma_f32_16x16x32_bf16 v[68:71], v[208:211], v[164:167], v[68:71]
	ds_read_b128 v[220:223], v247 offset:51200
	v_mfma_f32_16x16x32_bf16 v[68:71], v[204:207], v[160:163], v[68:71]
	ds_read_b128 v[224:227], v248 offset:51200
	v_mfma_f32_16x16x32_bf16 v[76:79], v[204:207], v[168:171], v[76:79]
	s_add_u32 s30, s30, s4
	s_addc_u32 s31, s31, s5
	s_add_u32 s56, s56, s4
	s_addc_u32 s57, s57, s5
	v_mfma_f32_16x16x32_bf16 v[76:79], v[208:211], v[172:175], v[76:79]
	s_add_u32 s32, s32, s4
	s_addc_u32 s33, s33, s5
	s_add_u32 s58, s58, s4
	s_addc_u32 s59, s59, s5
	v_mfma_f32_16x16x32_bf16 v[72:75], v[200:203], v[172:175], v[72:75]
	v_mfma_f32_16x16x32_bf16 v[72:75], v[196:199], v[168:171], v[72:75]
	v_mfma_f32_16x16x32_bf16 v[80:83], v[196:199], v[176:179], v[80:83]
	v_mfma_f32_16x16x32_bf16 v[80:83], v[200:203], v[180:183], v[80:83]
	v_mfma_f32_16x16x32_bf16 v[84:87], v[208:211], v[180:183], v[84:87]
	v_mfma_f32_16x16x32_bf16 v[84:87], v[204:207], v[176:179], v[84:87]
	v_mfma_f32_16x16x32_bf16 v[92:95], v[204:207], v[188:191], v[92:95]
	v_mfma_f32_16x16x32_bf16 v[92:95], v[208:211], v[192:195], v[92:95]
	v_mfma_f32_16x16x32_bf16 v[88:91], v[200:203], v[192:195], v[88:91]
	v_mfma_f32_16x16x32_bf16 v[88:91], v[196:199], v[188:191], v[88:91]
	s_waitcnt vmcnt(8)
	s_waitcnt lgkmcnt(0)
	s_barrier
; #define PG8_STAGE(bufoff, gbase, voff) do { _Pragma("unroll") for (int _i = 0; _i < 2; ++_i) \
;         __builtin_amdgcn_global_load_lds((const unsigned*)((const char*)(gbase) + (voff)[_i]), (PG8_LAS unsigned*)(lds + (bufoff) + ldsw + _i * 8192), 16, 0, 0); } while (0)
; #define PG8_LDA(dst, b, h) do { _Pragma("unroll") for (int m = 0; m < 4; ++m) _Pragma("unroll") for (int k = 0; k < 2; ++k) dst[m][k] = *(const PG8_LAS bf16x8*)(lds + PG8_SA(b, h) + aoff + m * 2048 + k * 1024); } while (0)
; #define PG8_LDB(dst, b, h) do { _Pragma("unroll") for (int n = 0; n < 2; ++n) _Pragma("unroll") for (int k = 0; k < 2; ++k) dst[n][k] = *(const PG8_LAS bf16x8*)(lds + PG8_SB(b, h) + boff + n * 2048 + k * 1024); } while (0)
; #define PG8_MMA(ai, bj, At, Bt) do { __builtin_amdgcn_s_setprio(1); _Pragma("unroll") for (int m = 0; m < 4; ++m) _Pragma("unroll") for (int n = 0; n < 2; ++n) _Pragma("unroll") for (int k = 0; k < 2; ++k) \
;         acc[ai][bj][m][n] = __builtin_amdgcn_mfma_f32_16x16x32_bf16(Bt[n][k], At[m][k], acc[ai][bj][m][n], 0, 0, 0); __builtin_amdgcn_s_setprio(0); } while (0)
; #define PG8_WAIT_V(n) asm volatile("s_waitcnt vmcnt(" #n ")" ::: "memory")
; template <class Epi, class Sched, bool ALIGN_EPI = false, bool SP2 = false>
; __device__ __forceinline__ void gemm_phase(PG8_LAS unsigned char* lds, const Gemm g, const Sched& S, const Epi& E) {
;     ...
;             PG8_LDB(B0, 0, 0); PG8_LDB(B1, 0, 1); PG8_SCHED; PG8_LDA(At, 0, 0); PG8_STAGE(PG8_SA(1, 1), a1 + hstep, voffA);
;             PG8_WAIT_V(8); PG8_WAIT_L(0); PG8_BAR; PG8_MMA(0, 0, At, B0); PG8_MMA(0, 1, At, B1); PG8_BAR; PG8_SCHED;
;             PG8_LDA(At, 0, 1); PG8_STAGE(PG8_SB(0, 0), b2, voffB); PG8_STAGE(PG8_SB(0, 1), b2 + hstep, voffB); PG8_STAGE(PG8_SA(0, 0), a2, voffA);
;             PG8_WAIT_V(8); PG8_WAIT_L(0); PG8_BAR; PG8_MMA(1, 0, At, B0); PG8_MMA(1, 1, At, B1); PG8_BAR; PG8_SCHED;
;             PG8_LDB(B0, 1, 0); PG8_LDB(B1, 1, 1); PG8_SCHED; PG8_LDA(At, 1, 0); PG8_STAGE(PG8_SA(0, 1), a2 + hstep, voffA);
;             PG8_WAIT_V(8); PG8_WAIT_L(0); PG8_BAR; PG8_MMA(0, 0, At, B0); PG8_MMA(0, 1, At, B1); PG8_BAR; PG8_SCHED;
;             PG8_LDA(At, 1, 1); PG8_STAGE(PG8_SB(1, 0), b3, voffB); PG8_STAGE(PG8_SB(1, 1), b3 + hstep, voffB); PG8_STAGE(PG8_SA(1, 0), a3, voffA);
;             PG8_WAIT_V(8); PG8_WAIT_L(0); PG8_BAR; PG8_MMA(1, 0, At, B0); PG8_MMA(1, 1, At, B1); PG8_BAR; PG8_SCHED;
	v_mfma_f32_16x16x32_bf16 v[32:35], v[212:215], v[128:131], v[32:35]
	ds_read_b128 v[196:199], v247 offset:32768
	v_mfma_f32_16x16x32_bf16 v[32:35], v[216:219], v[132:135], v[32:35]
	ds_read_b128 v[200:203], v248 offset:32768
	v_mfma_f32_16x16x32_bf16 v[36:39], v[224:227], v[132:135], v[36:39]
	ds_read_b128 v[204:207], v247 offset:34816
	v_mfma_f32_16x16x32_bf16 v[36:39], v[220:223], v[128:131], v[36:39]
	ds_read_b128 v[208:211], v248 offset:34816
	v_mfma_f32_16x16x32_bf16 v[44:47], v[220:223], v[136:139], v[44:47]
	s_add_i32 m0, s35, 0x8000
	v_mfma_f32_16x16x32_bf16 v[44:47], v[224:227], v[140:143], v[44:47]
	global_load_lds_dwordx4 v249, s[30:31]
	v_mfma_f32_16x16x32_bf16 v[40:43], v[216:219], v[140:143], v[40:43]
	s_add_i32 m0, s35, 0xa000
	v_mfma_f32_16x16x32_bf16 v[40:43], v[212:215], v[136:139], v[40:43]
	global_load_lds_dwordx4 v250, s[30:31]
	v_mfma_f32_16x16x32_bf16 v[48:51], v[212:215], v[144:147], v[48:51]
	s_add_i32 m0, s35, 0x1c000
	v_mfma_f32_16x16x32_bf16 v[48:51], v[216:219], v[148:151], v[48:51]
	global_load_lds_dwordx4 v251, s[58:59]
	v_mfma_f32_16x16x32_bf16 v[52:55], v[224:227], v[148:151], v[52:55]
	s_add_i32 m0, s35, 0x1e000
	v_mfma_f32_16x16x32_bf16 v[52:55], v[220:223], v[144:147], v[52:55]
	global_load_lds_dwordx4 v252, s[58:59]
	v_mfma_f32_16x16x32_bf16 v[60:63], v[220:223], v[152:155], v[60:63]
	ds_read_b128 v[160:163], v245 offset:49152
	v_mfma_f32_16x16x32_bf16 v[60:63], v[224:227], v[156:159], v[60:63]
	ds_read_b128 v[164:167], v246 offset:49152
	v_mfma_f32_16x16x32_bf16 v[56:59], v[216:219], v[156:159], v[56:59]
	ds_read_b128 v[168:171], v245 offset:51200
	v_mfma_f32_16x16x32_bf16 v[56:59], v[212:215], v[152:155], v[56:59]
	ds_read_b128 v[172:175], v246 offset:51200
	s_waitcnt lgkmcnt(4)
	v_mfma_f32_16x16x32_bf16 v[0:3], v[196:199], v[128:131], v[0:3]
	ds_read_b128 v[176:179], v245 offset:53248
	v_mfma_f32_16x16x32_bf16 v[0:3], v[200:203], v[132:135], v[0:3]
	ds_read_b128 v[180:183], v246 offset:53248
	v_mfma_f32_16x16x32_bf16 v[4:7], v[208:211], v[132:135], v[4:7]
	ds_read_b128 v[188:191], v245 offset:55296
	v_mfma_f32_16x16x32_bf16 v[4:7], v[204:207], v[128:131], v[4:7]
	ds_read_b128 v[192:195], v246 offset:55296
	v_mfma_f32_16x16x32_bf16 v[12:15], v[204:207], v[136:139], v[12:15]
	v_mfma_f32_16x16x32_bf16 v[12:15], v[208:211], v[140:143], v[12:15]
	v_mfma_f32_16x16x32_bf16 v[8:11], v[200:203], v[140:143], v[8:11]
	v_mfma_f32_16x16x32_bf16 v[8:11], v[196:199], v[136:139], v[8:11]
	v_mfma_f32_16x16x32_bf16 v[16:19], v[196:199], v[144:147], v[16:19]
	v_mfma_f32_16x16x32_bf16 v[16:19], v[200:203], v[148:151], v[16:19]
	v_mfma_f32_16x16x32_bf16 v[20:23], v[208:211], v[148:151], v[20:23]
	v_mfma_f32_16x16x32_bf16 v[20:23], v[204:207], v[144:147], v[20:23]
	v_mfma_f32_16x16x32_bf16 v[28:31], v[204:207], v[152:155], v[28:31]
	v_mfma_f32_16x16x32_bf16 v[28:31], v[208:211], v[156:159], v[28:31]
	v_mfma_f32_16x16x32_bf16 v[24:27], v[200:203], v[156:159], v[24:27]
	v_mfma_f32_16x16x32_bf16 v[24:27], v[196:199], v[152:155], v[24:27]
	s_waitcnt vmcnt(8)
	s_waitcnt lgkmcnt(0)
	s_barrier
	v_mfma_f32_16x16x32_bf16 v[64:67], v[196:199], v[160:163], v[64:67]
	s_add_i32 m0, s35, 0xc000
	v_mfma_f32_16x16x32_bf16 v[64:67], v[200:203], v[164:167], v[64:67]
	global_load_lds_dwordx4 v249, s[56:57]
	v_mfma_f32_16x16x32_bf16 v[68:71], v[208:211], v[164:167], v[68:71]
	s_add_i32 m0, s35, 0xe000
	v_mfma_f32_16x16x32_bf16 v[68:71], v[204:207], v[160:163], v[68:71]
	global_load_lds_dwordx4 v250, s[56:57]
	v_mfma_f32_16x16x32_bf16 v[76:79], v[204:207], v[168:171], v[76:79]
	s_add_i32 m0, s35, 0x18000
	v_mfma_f32_16x16x32_bf16 v[76:79], v[208:211], v[172:175], v[76:79]
	global_load_lds_dwordx4 v251, s[32:33]
	v_mfma_f32_16x16x32_bf16 v[72:75], v[200:203], v[172:175], v[72:75]
	s_add_i32 m0, s35, 0x1a000
	v_mfma_f32_16x16x32_bf16 v[72:75], v[196:199], v[168:171], v[72:75]
	global_load_lds_dwordx4 v252, s[32:33]
	v_mfma_f32_16x16x32_bf16 v[80:83], v[196:199], v[176:179], v[80:83]
	ds_read_b128 v[128:131], v245 offset:0
	v_mfma_f32_16x16x32_bf16 v[80:83], v[200:203], v[180:183], v[80:83]
	ds_read_b128 v[132:135], v246 offset:0
	v_mfma_f32_16x16x32_bf16 v[84:87], v[208:211], v[180:183], v[84:87]
	ds_read_b128 v[136:139], v245 offset:2048
	v_mfma_f32_16x16x32_bf16 v[84:87], v[204:207], v[176:179], v[84:87]
	ds_read_b128 v[140:143], v246 offset:2048
	v_mfma_f32_16x16x32_bf16 v[92:95], v[204:207], v[188:191], v[92:95]
	ds_read_b128 v[144:147], v245 offset:4096
	v_mfma_f32_16x16x32_bf16 v[92:95], v[208:211], v[192:195], v[92:95]
	ds_read_b128 v[148:151], v246 offset:4096
	v_mfma_f32_16x16x32_bf16 v[88:91], v[200:203], v[192:195], v[88:91]
	ds_read_b128 v[152:155], v245 offset:6144
	v_mfma_f32_16x16x32_bf16 v[88:91], v[196:199], v[188:191], v[88:91]
	ds_read_b128 v[156:159], v246 offset:6144
	v_mfma_f32_16x16x32_bf16 v[96:99], v[212:215], v[160:163], v[96:99]
	ds_read_b128 v[196:199], v247 offset:0
	v_mfma_f32_16x16x32_bf16 v[96:99], v[216:219], v[164:167], v[96:99]
	ds_read_b128 v[200:203], v248 offset:0
	v_mfma_f32_16x16x32_bf16 v[100:103], v[224:227], v[164:167], v[100:103]
	ds_read_b128 v[204:207], v247 offset:2048
	v_mfma_f32_16x16x32_bf16 v[100:103], v[220:223], v[160:163], v[100:103]
	ds_read_b128 v[208:211], v248 offset:2048
	v_mfma_f32_16x16x32_bf16 v[108:111], v[220:223], v[168:171], v[108:111]
	s_add_u32 s30, s30, s4
	s_addc_u32 s31, s31, s5
	s_add_u32 s56, s56, s4
	s_addc_u32 s57, s57, s5
	v_mfma_f32_16x16x32_bf16 v[108:111], v[224:227], v[172:175], v[108:111]
	s_add_u32 s32, s32, s4
	s_addc_u32 s33, s33, s5
	s_add_u32 s58, s58, s4
	s_addc_u32 s59, s59, s5
	v_mfma_f32_16x16x32_bf16 v[104:107], v[216:219], v[172:175], v[104:107]
	v_mfma_f32_16x16x32_bf16 v[104:107], v[212:215], v[168:171], v[104:107]
	v_mfma_f32_16x16x32_bf16 v[112:115], v[212:215], v[176:179], v[112:115]
	v_mfma_f32_16x16x32_bf16 v[112:115], v[216:219], v[180:183], v[112:115]
	v_mfma_f32_16x16x32_bf16 v[116:119], v[224:227], v[180:183], v[116:119]
	v_mfma_f32_16x16x32_bf16 v[116:119], v[220:223], v[176:179], v[116:119]
	v_mfma_f32_16x16x32_bf16 v[124:127], v[220:223], v[188:191], v[124:127]
	v_mfma_f32_16x16x32_bf16 v[124:127], v[224:227], v[192:195], v[124:127]
	v_mfma_f32_16x16x32_bf16 v[120:123], v[216:219], v[192:195], v[120:123]
	v_mfma_f32_16x16x32_bf16 v[120:123], v[212:215], v[188:191], v[120:123]
	s_add_i32 s34, s34, -1
	s_cmp_lg_u32 s34, 1
	s_cbranch_scc1 .Lp1_nosw0
	s_add_u32 s45, s16, 1
	s_and_b32 s40, s45, 1
	s_lshl_b32 s4, s40, 8
	s_sub_u32 s4, 128, s4
	s_sub_u32 s5, 0, s40
	s_mul_i32 s8, s40, 3968
	s_add_u32 s30, s26, s8
	s_addc_u32 s31, s27, 0
	s_add_u32 s32, s28, s8
	s_addc_u32 s33, s29, 0
	s_add_u32 s56, s30, 0x80000
	s_addc_u32 s57, s31, 0
	s_add_u32 s58, s32, 0x80000
	s_addc_u32 s59, s33, 0

; #define PG8_STAGE(bufoff, gbase, voff) do { _Pragma("unroll") for (int _i = 0; _i < 2; ++_i) \
;         __builtin_amdgcn_global_load_lds((const unsigned*)((const char*)(gbase) + (voff)[_i]), (PG8_LAS unsigned*)(lds + (bufoff) + ldsw + _i * 8192), 16, 0, 0); } while (0)
; #define PG8_LDA(dst, b, h) do { _Pragma("unroll") for (int m = 0; m < 4; ++m) _Pragma("unroll") for (int k = 0; k < 2; ++k) dst[m][k] = *(const PG8_LAS bf16x8*)(lds + PG8_SA(b, h) + aoff + m * 2048 + k * 1024); } while (0)
; #define PG8_LDB(dst, b, h) do { _Pragma("unroll") for (int n = 0; n < 2; ++n) _Pragma("unroll") for (int k = 0; k < 2; ++k) dst[n][k] = *(const PG8_LAS bf16x8*)(lds + PG8_SB(b, h) + boff + n * 2048 + k * 1024); } while (0)
; #define PG8_MMA(ai, bj, At, Bt) do { __builtin_amdgcn_s_setprio(1); _Pragma("unroll") for (int m = 0; m < 4; ++m) _Pragma("unroll") for (int n = 0; n < 2; ++n) _Pragma("unroll") for (int k = 0; k < 2; ++k) \
;         acc[ai][bj][m][n] = __builtin_amdgcn_mfma_f32_16x16x32_bf16(Bt[n][k], At[m][k], acc[ai][bj][m][n], 0, 0, 0); __builtin_amdgcn_s_setprio(0); } while (0)
; #define PG8_WAIT_V(n) asm volatile("s_waitcnt vmcnt(" #n ")" ::: "memory")
; template <class Epi, class Sched, bool ALIGN_EPI = false, bool SP2 = false>
; __device__ __forceinline__ void gemm_phase(PG8_LAS unsigned char* lds, const Gemm g, const Sched& S, const Epi& E) {
;     ...
;             PG8_LDB(B0, 0, 0); PG8_LDB(B1, 0, 1); PG8_SCHED; PG8_LDA(At, 0, 0); PG8_STAGE(PG8_SA(1, 1), a1 + hstep, voffA);
;             PG8_WAIT_V(8); PG8_WAIT_L(0); PG8_BAR; PG8_MMA(0, 0, At, B0); PG8_MMA(0, 1, At, B1); PG8_BAR; PG8_SCHED;
;             PG8_LDA(At, 0, 1); PG8_STAGE(PG8_SB(0, 0), b2, voffB); PG8_STAGE(PG8_SB(0, 1), b2 + hstep, voffB); PG8_STAGE(PG8_SA(0, 0), a2, voffA);
;             PG8_WAIT_V(8); PG8_WAIT_L(0); PG8_BAR; PG8_MMA(1, 0, At, B0); PG8_MMA(1, 1, At, B1); PG8_BAR; PG8_SCHED;
;             PG8_LDB(B0, 1, 0); PG8_LDB(B1, 1, 1); PG8_SCHED; PG8_LDA(At, 1, 0); PG8_STAGE(PG8_SA(0, 1), a2 + hstep, voffA);
;             PG8_WAIT_V(8); PG8_WAIT_L(0); PG8_BAR; PG8_MMA(0, 0, At, B0); PG8_MMA(0, 1, At, B1); PG8_BAR; PG8_SCHED;
;             PG8_LDA(At, 1, 1); PG8_STAGE(PG8_SB(1, 0), b3, voffB); PG8_STAGE(PG8_SB(1, 1), b3 + hstep, voffB); PG8_STAGE(PG8_SA(1, 0), a3, voffA);
;             PG8_WAIT_V(8); PG8_WAIT_L(0); PG8_BAR; PG8_MMA(1, 0, At, B0); PG8_MMA(1, 1, At, B1); PG8_BAR; PG8_SCHED;
.Lp1_kloop1:
	s_waitcnt vmcnt(8)
	s_waitcnt lgkmcnt(0)
	s_barrier
	v_mfma_f32_16x16x32_bf16 v[0:3], v[196:199], v[128:131], v[0:3]
	ds_read_b128 v[212:215], v247 offset:16384
	v_mfma_f32_16x16x32_bf16 v[0:3], v[200:203], v[132:135], v[0:3]
	ds_read_b128 v[216:219], v248 offset:16384
	v_mfma_f32_16x16x32_bf16 v[4:7], v[208:211], v[132:135], v[4:7]
	ds_read_b128 v[220:223], v247 offset:18432
	v_mfma_f32_16x16x32_bf16 v[4:7], v[204:207], v[128:131], v[4:7]
	ds_read_b128 v[224:227], v248 offset:18432
	v_mfma_f32_16x16x32_bf16 v[12:15], v[204:207], v[136:139], v[12:15]
	ds_read_b128 v[160:163], v245 offset:16384
	v_mfma_f32_16x16x32_bf16 v[12:15], v[208:211], v[140:143], v[12:15]
	ds_read_b128 v[164:167], v246 offset:16384
	v_mfma_f32_16x16x32_bf16 v[8:11], v[200:203], v[140:143], v[8:11]
	ds_read_b128 v[168:171], v245 offset:18432
	v_mfma_f32_16x16x32_bf16 v[8:11], v[196:199], v[136:139], v[8:11]
	ds_read_b128 v[172:175], v246 offset:18432
	v_mfma_f32_16x16x32_bf16 v[16:19], v[196:199], v[144:147], v[16:19]
	ds_read_b128 v[176:179], v245 offset:20480
	v_mfma_f32_16x16x32_bf16 v[16:19], v[200:203], v[148:151], v[16:19]
	ds_read_b128 v[180:183], v246 offset:20480
	v_mfma_f32_16x16x32_bf16 v[20:23], v[208:211], v[148:151], v[20:23]
	ds_read_b128 v[188:191], v245 offset:22528
	v_mfma_f32_16x16x32_bf16 v[20:23], v[204:207], v[144:147], v[20:23]
	ds_read_b128 v[192:195], v246 offset:22528
	v_mfma_f32_16x16x32_bf16 v[28:31], v[204:207], v[152:155], v[28:31]
	v_mfma_f32_16x16x32_bf16 v[28:31], v[208:211], v[156:159], v[28:31]
	v_mfma_f32_16x16x32_bf16 v[24:27], v[200:203], v[156:159], v[24:27]
	v_mfma_f32_16x16x32_bf16 v[24:27], v[196:199], v[152:155], v[24:27]
	s_waitcnt lgkmcnt(8)
	v_mfma_f32_16x16x32_bf16 v[32:35], v[212:215], v[128:131], v[32:35]
	v_mfma_f32_16x16x32_bf16 v[32:35], v[216:219], v[132:135], v[32:35]
	s_add_i32 m0, s35, 0x0
	v_mfma_f32_16x16x32_bf16 v[36:39], v[224:227], v[132:135], v[36:39]
	global_load_lds_dwordx4 v249, s[30:31]
	v_mfma_f32_16x16x32_bf16 v[36:39], v[220:223], v[128:131], v[36:39]
	v_mfma_f32_16x16x32_bf16 v[44:47], v[220:223], v[136:139], v[44:47]
	s_add_i32 m0, s35, 0x2000
	v_mfma_f32_16x16x32_bf16 v[44:47], v[224:227], v[140:143], v[44:47]
	global_load_lds_dwordx4 v250, s[30:31]
	v_mfma_f32_16x16x32_bf16 v[40:43], v[216:219], v[140:143], v[40:43]
	v_mfma_f32_16x16x32_bf16 v[40:43], v[212:215], v[136:139], v[40:43]
	s_add_i32 m0, s35, 0x10000
	v_mfma_f32_16x16x32_bf16 v[48:51], v[212:215], v[144:147], v[48:51]
	global_load_lds_dwordx4 v251, s[32:33]
	v_mfma_f32_16x16x32_bf16 v[48:51], v[216:219], v[148:151], v[48:51]
	v_mfma_f32_16x16x32_bf16 v[52:55], v[224:227], v[148:151], v[52:55]
	s_add_i32 m0, s35, 0x12000
	v_mfma_f32_16x16x32_bf16 v[52:55], v[220:223], v[144:147], v[52:55]
	global_load_lds_dwordx4 v252, s[32:33]
	v_mfma_f32_16x16x32_bf16 v[60:63], v[220:223], v[152:155], v[60:63]
	v_mfma_f32_16x16x32_bf16 v[60:63], v[224:227], v[156:159], v[60:63]
	v_mfma_f32_16x16x32_bf16 v[56:59], v[216:219], v[156:159], v[56:59]
	v_mfma_f32_16x16x32_bf16 v[56:59], v[212:215], v[152:155], v[56:59]
	s_waitcnt vmcnt(8)
	s_waitcnt lgkmcnt(0)
	s_barrier
	v_mfma_f32_16x16x32_bf16 v[96:99], v[212:215], v[160:163], v[96:99]
	ds_read_b128 v[128:131], v245 offset:32768
	v_mfma_f32_16x16x32_bf16 v[96:99], v[216:219], v[164:167], v[96:99]
	ds_read_b128 v[132:135], v246 offset:32768
	v_mfma_f32_16x16x32_bf16 v[100:103], v[224:227], v[164:167], v[100:103]
	ds_read_b128 v[136:139], v245 offset:34816
	v_mfma_f32_16x16x32_bf16 v[100:103], v[220:223], v[160:163], v[100:103]
	ds_read_b128 v[140:143], v246 offset:34816
	v_mfma_f32_16x16x32_bf16 v[108:111], v[220:223], v[168:171], v[108:111]
	ds_read_b128 v[144:147], v245 offset:36864
	v_mfma_f32_16x16x32_bf16 v[108:111], v[224:227], v[172:175], v[108:111]
	ds_read_b128 v[148:151], v246 offset:36864
	v_mfma_f32_16x16x32_bf16 v[104:107], v[216:219], v[172:175], v[104:107]
	ds_read_b128 v[152:155], v245 offset:38912
	v_mfma_f32_16x16x32_bf16 v[104:107], v[212:215], v[168:171], v[104:107]
	ds_read_b128 v[156:159], v246 offset:38912
	v_mfma_f32_16x16x32_bf16 v[112:115], v[212:215], v[176:179], v[112:115]
	v_mfma_f32_16x16x32_bf16 v[112:115], v[216:219], v[180:183], v[112:115]
	v_mfma_f32_16x16x32_bf16 v[116:119], v[224:227], v[180:183], v[116:119]
	v_mfma_f32_16x16x32_bf16 v[116:119], v[220:223], v[176:179], v[116:119]
	v_mfma_f32_16x16x32_bf16 v[124:127], v[220:223], v[188:191], v[124:127]
	v_mfma_f32_16x16x32_bf16 v[124:127], v[224:227], v[192:195], v[124:127]
	v_mfma_f32_16x16x32_bf16 v[120:123], v[216:219], v[192:195], v[120:123]
	v_mfma_f32_16x16x32_bf16 v[120:123], v[212:215], v[188:191], v[120:123]
	v_mfma_f32_16x16x32_bf16 v[64:67], v[196:199], v[160:163], v[64:67]
	ds_read_b128 v[212:215], v247 offset:49152
	v_mfma_f32_16x16x32_bf16 v[64:67], v[200:203], v[164:167], v[64:67]
	ds_read_b128 v[216:219], v248 offset:49152
	v_mfma_f32_16x16x32_bf16 v[68:71], v[208:211], v[164:167], v[68:71]
	ds_read_b128 v[220:223], v247 offset:51200
	v_mfma_f32_16x16x32_bf16 v[68:71], v[204:207], v[160:163], v[68:71]
	ds_read_b128 v[224:227], v248 offset:51200
	v_mfma_f32_16x16x32_bf16 v[76:79], v[204:207], v[168:171], v[76:79]
	s_add_i32 m0, s35, 0x4000
	v_mfma_f32_16x16x32_bf16 v[76:79], v[208:211], v[172:175], v[76:79]
	global_load_lds_dwordx4 v249, s[56:57]
	v_mfma_f32_16x16x32_bf16 v[72:75], v[200:203], v[172:175], v[72:75]
	s_add_i32 m0, s35, 0x6000
	v_mfma_f32_16x16x32_bf16 v[72:75], v[196:199], v[168:171], v[72:75]
	global_load_lds_dwordx4 v250, s[56:57]
	v_mfma_f32_16x16x32_bf16 v[80:83], v[196:199], v[176:179], v[80:83]
	s_add_i32 m0, s35, 0x14000
	v_mfma_f32_16x16x32_bf16 v[80:83], v[200:203], v[180:183], v[80:83]
	global_load_lds_dwordx4 v251, s[58:59]
	v_mfma_f32_16x16x32_bf16 v[84:87], v[208:211], v[180:183], v[84:87]
	s_add_i32 m0, s35, 0x16000
	v_mfma_f32_16x16x32_bf16 v[84:87], v[204:207], v[176:179], v[84:87]
	global_load_lds_dwordx4 v252, s[58:59]
	v_mfma_f32_16x16x32_bf16 v[92:95], v[204:207], v[188:191], v[92:95]
	s_add_u32 s30, s30, s4
	s_addc_u32 s31, s31, s5
	s_add_u32 s56, s56, s4
	s_addc_u32 s57, s57, s5
	v_mfma_f32_16x16x32_bf16 v[92:95], v[208:211], v[192:195], v[92:95]
	s_add_u32 s32, s32, s4
	s_addc_u32 s33, s33, s5
	s_add_u32 s58, s58, s4
	s_addc_u32 s59, s59, s5
	v_mfma_f32_16x16x32_bf16 v[88:91], v[200:203], v[192:195], v[88:91]
	v_mfma_f32_16x16x32_bf16 v[88:91], v[196:199], v[188:191], v[88:91]
	s_waitcnt vmcnt(8)
	s_waitcnt lgkmcnt(0)
	s_barrier
; #define PG8_STAGE(bufoff, gbase, voff) do { _Pragma("unroll") for (int _i = 0; _i < 2; ++_i) \
;         __builtin_amdgcn_global_load_lds((const unsigned*)((const char*)(gbase) + (voff)[_i]), (PG8_LAS unsigned*)(lds + (bufoff) + ldsw + _i * 8192), 16, 0, 0); } while (0)
; #define PG8_LDA(dst, b, h) do { _Pragma("unroll") for (int m = 0; m < 4; ++m) _Pragma("unroll") for (int k = 0; k < 2; ++k) dst[m][k] = *(const PG8_LAS bf16x8*)(lds + PG8_SA(b, h) + aoff + m * 2048 + k * 1024); } while (0)
; #define PG8_LDB(dst, b, h) do { _Pragma("unroll") for (int n = 0; n < 2; ++n) _Pragma("unroll") for (int k = 0; k < 2; ++k) dst[n][k] = *(const PG8_LAS bf16x8*)(lds + PG8_SB(b, h) + boff + n * 2048 + k * 1024); } while (0)
; #define PG8_MMA(ai, bj, At, Bt) do { __builtin_amdgcn_s_setprio(1); _Pragma("unroll") for (int m = 0; m < 4; ++m) _Pragma("unroll") for (int n = 0; n < 2; ++n) _Pragma("unroll") for (int k = 0; k < 2; ++k) \
;         acc[ai][bj][m][n] = __builtin_amdgcn_mfma_f32_16x16x32_bf16(Bt[n][k], At[m][k], acc[ai][bj][m][n], 0, 0, 0); __builtin_amdgcn_s_setprio(0); } while (0)
; #define PG8_WAIT_V(n) asm volatile("s_waitcnt vmcnt(" #n ")" ::: "memory")
; template <class Epi, class Sched, bool ALIGN_EPI = false, bool SP2 = false>
; __device__ __forceinline__ void gemm_phase(PG8_LAS unsigned char* lds, const Gemm g, const Sched& S, const Epi& E) {
;     ...
;             PG8_LDB(B0, 0, 0); PG8_LDB(B1, 0, 1); PG8_SCHED; PG8_LDA(At, 0, 0); PG8_STAGE(PG8_SA(1, 1), a1 + hstep, voffA);
;             PG8_WAIT_V(8); PG8_WAIT_L(0); PG8_BAR; PG8_MMA(0, 0, At, B0); PG8_MMA(0, 1, At, B1); PG8_BAR; PG8_SCHED;
;             PG8_LDA(At, 0, 1); PG8_STAGE(PG8_SB(0, 0), b2, voffB); PG8_STAGE(PG8_SB(0, 1), b2 + hstep, voffB); PG8_STAGE(PG8_SA(0, 0), a2, voffA);
;             PG8_WAIT_V(8); PG8_WAIT_L(0); PG8_BAR; PG8_MMA(1, 0, At, B0); PG8_MMA(1, 1, At, B1); PG8_BAR; PG8_SCHED;
;             PG8_LDB(B0, 1, 0); PG8_LDB(B1, 1, 1); PG8_SCHED; PG8_LDA(At, 1, 0); PG8_STAGE(PG8_SA(0, 1), a2 + hstep, voffA);
;             PG8_WAIT_V(8); PG8_WAIT_L(0); PG8_BAR; PG8_MMA(0, 0, At, B0); PG8_MMA(0, 1, At, B1); PG8_BAR; PG8_SCHED;
;             PG8_LDA(At, 1, 1); PG8_STAGE(PG8_SB(1, 0), b3, voffB); PG8_STAGE(PG8_SB(1, 1), b3 + hstep, voffB); PG8_STAGE(PG8_SA(1, 0), a3, voffA);
;             PG8_WAIT_V(8); PG8_WAIT_L(0); PG8_BAR; PG8_MMA(1, 0, At, B0); PG8_MMA(1, 1, At, B1); PG8_BAR; PG8_SCHED;
	v_mfma_f32_16x16x32_bf16 v[32:35], v[212:215], v[128:131], v[32:35]
	ds_read_b128 v[196:199], v247 offset:32768
	v_mfma_f32_16x16x32_bf16 v[32:35], v[216:219], v[132:135], v[32:35]
	ds_read_b128 v[200:203], v248 offset:32768
	v_mfma_f32_16x16x32_bf16 v[36:39], v[224:227], v[132:135], v[36:39]
	ds_read_b128 v[204:207], v247 offset:34816
	v_mfma_f32_16x16x32_bf16 v[36:39], v[220:223], v[128:131], v[36:39]
	ds_read_b128 v[208:211], v248 offset:34816
	v_mfma_f32_16x16x32_bf16 v[44:47], v[220:223], v[136:139], v[44:47]
	ds_read_b128 v[160:163], v245 offset:49152
	v_mfma_f32_16x16x32_bf16 v[44:47], v[224:227], v[140:143], v[44:47]
	ds_read_b128 v[164:167], v246 offset:49152
	v_mfma_f32_16x16x32_bf16 v[40:43], v[216:219], v[140:143], v[40:43]
	ds_read_b128 v[168:171], v245 offset:51200
	v_mfma_f32_16x16x32_bf16 v[40:43], v[212:215], v[136:139], v[40:43]
	ds_read_b128 v[172:175], v246 offset:51200
	v_mfma_f32_16x16x32_bf16 v[48:51], v[212:215], v[144:147], v[48:51]
	ds_read_b128 v[176:179], v245 offset:53248
	v_mfma_f32_16x16x32_bf16 v[48:51], v[216:219], v[148:151], v[48:51]
	ds_read_b128 v[180:183], v246 offset:53248
	v_mfma_f32_16x16x32_bf16 v[52:55], v[224:227], v[148:151], v[52:55]
	ds_read_b128 v[188:191], v245 offset:55296
	v_mfma_f32_16x16x32_bf16 v[52:55], v[220:223], v[144:147], v[52:55]
	ds_read_b128 v[192:195], v246 offset:55296
	v_mfma_f32_16x16x32_bf16 v[60:63], v[220:223], v[152:155], v[60:63]
	v_mfma_f32_16x16x32_bf16 v[60:63], v[224:227], v[156:159], v[60:63]
	v_mfma_f32_16x16x32_bf16 v[56:59], v[216:219], v[156:159], v[56:59]
	v_mfma_f32_16x16x32_bf16 v[56:59], v[212:215], v[152:155], v[56:59]
	s_waitcnt lgkmcnt(8)
	v_mfma_f32_16x16x32_bf16 v[0:3], v[196:199], v[128:131], v[0:3]
	v_mfma_f32_16x16x32_bf16 v[0:3], v[200:203], v[132:135], v[0:3]
	s_add_i32 m0, s35, 0x8000
	v_mfma_f32_16x16x32_bf16 v[4:7], v[208:211], v[132:135], v[4:7]
	global_load_lds_dwordx4 v249, s[30:31]
	v_mfma_f32_16x16x32_bf16 v[4:7], v[204:207], v[128:131], v[4:7]
	v_mfma_f32_16x16x32_bf16 v[12:15], v[204:207], v[136:139], v[12:15]
	s_add_i32 m0, s35, 0xa000
	v_mfma_f32_16x16x32_bf16 v[12:15], v[208:211], v[140:143], v[12:15]
	global_load_lds_dwordx4 v250, s[30:31]
	v_mfma_f32_16x16x32_bf16 v[8:11], v[200:203], v[140:143], v[8:11]
	v_mfma_f32_16x16x32_bf16 v[8:11], v[196:199], v[136:139], v[8:11]
	s_add_i32 m0, s35, 0x1c000
	v_mfma_f32_16x16x32_bf16 v[16:19], v[196:199], v[144:147], v[16:19]
	global_load_lds_dwordx4 v251, s[58:59]
	v_mfma_f32_16x16x32_bf16 v[16:19], v[200:203], v[148:151], v[16:19]
	v_mfma_f32_16x16x32_bf16 v[20:23], v[208:211], v[148:151], v[20:23]
	s_add_i32 m0, s35, 0x1e000
	v_mfma_f32_16x16x32_bf16 v[20:23], v[204:207], v[144:147], v[20:23]
	global_load_lds_dwordx4 v252, s[58:59]
	v_mfma_f32_16x16x32_bf16 v[28:31], v[204:207], v[152:155], v[28:31]
	v_mfma_f32_16x16x32_bf16 v[28:31], v[208:211], v[156:159], v[28:31]
	v_mfma_f32_16x16x32_bf16 v[24:27], v[200:203], v[156:159], v[24:27]
	v_mfma_f32_16x16x32_bf16 v[24:27], v[196:199], v[152:155], v[24:27]
	s_waitcnt vmcnt(8)
	s_waitcnt lgkmcnt(0)
	s_barrier
	v_mfma_f32_16x16x32_bf16 v[64:67], v[196:199], v[160:163], v[64:67]
	ds_read_b128 v[128:131], v245 offset:0
	v_mfma_f32_16x16x32_bf16 v[64:67], v[200:203], v[164:167], v[64:67]
	ds_read_b128 v[132:135], v246 offset:0
	v_mfma_f32_16x16x32_bf16 v[68:71], v[208:211], v[164:167], v[68:71]
	ds_read_b128 v[136:139], v245 offset:2048
	v_mfma_f32_16x16x32_bf16 v[68:71], v[204:207], v[160:163], v[68:71]
	ds_read_b128 v[140:143], v246 offset:2048
	v_mfma_f32_16x16x32_bf16 v[76:79], v[204:207], v[168:171], v[76:79]
	ds_read_b128 v[144:147], v245 offset:4096
	v_mfma_f32_16x16x32_bf16 v[76:79], v[208:211], v[172:175], v[76:79]
	ds_read_b128 v[148:151], v246 offset:4096
	v_mfma_f32_16x16x32_bf16 v[72:75], v[200:203], v[172:175], v[72:75]
	ds_read_b128 v[152:155], v245 offset:6144
	v_mfma_f32_16x16x32_bf16 v[72:75], v[196:199], v[168:171], v[72:75]
	ds_read_b128 v[156:159], v246 offset:6144
	v_mfma_f32_16x16x32_bf16 v[80:83], v[196:199], v[176:179], v[80:83]
	v_mfma_f32_16x16x32_bf16 v[80:83], v[200:203], v[180:183], v[80:83]
	v_mfma_f32_16x16x32_bf16 v[84:87], v[208:211], v[180:183], v[84:87]
	v_mfma_f32_16x16x32_bf16 v[84:87], v[204:207], v[176:179], v[84:87]
	v_mfma_f32_16x16x32_bf16 v[92:95], v[204:207], v[188:191], v[92:95]
	v_mfma_f32_16x16x32_bf16 v[92:95], v[208:211], v[192:195], v[92:95]
	v_mfma_f32_16x16x32_bf16 v[88:91], v[200:203], v[192:195], v[88:91]
	v_mfma_f32_16x16x32_bf16 v[88:91], v[196:199], v[188:191], v[88:91]
	v_mfma_f32_16x16x32_bf16 v[96:99], v[212:215], v[160:163], v[96:99]
	ds_read_b128 v[196:199], v247 offset:0
	v_mfma_f32_16x16x32_bf16 v[96:99], v[216:219], v[164:167], v[96:99]
	ds_read_b128 v[200:203], v248 offset:0
	v_mfma_f32_16x16x32_bf16 v[100:103], v[224:227], v[164:167], v[100:103]
	ds_read_b128 v[204:207], v247 offset:2048
	v_mfma_f32_16x16x32_bf16 v[100:103], v[220:223], v[160:163], v[100:103]
	ds_read_b128 v[208:211], v248 offset:2048
	v_mfma_f32_16x16x32_bf16 v[108:111], v[220:223], v[168:171], v[108:111]
	s_add_i32 m0, s35, 0xc000
	v_mfma_f32_16x16x32_bf16 v[108:111], v[224:227], v[172:175], v[108:111]
	global_load_lds_dwordx4 v249, s[56:57]
	v_mfma_f32_16x16x32_bf16 v[104:107], v[216:219], v[172:175], v[104:107]
	s_add_i32 m0, s35, 0xe000
	v_mfma_f32_16x16x32_bf16 v[104:107], v[212:215], v[168:171], v[104:107]
	global_load_lds_dwordx4 v250, s[56:57]
	v_mfma_f32_16x16x32_bf16 v[112:115], v[212:215], v[176:179], v[112:115]
	s_add_i32 m0, s35, 0x18000
	v_mfma_f32_16x16x32_bf16 v[112:115], v[216:219], v[180:183], v[112:115]
	global_load_lds_dwordx4 v251, s[32:33]
	v_mfma_f32_16x16x32_bf16 v[116:119], v[224:227], v[180:183], v[116:119]
	s_add_i32 m0, s35, 0x1a000
	v_mfma_f32_16x16x32_bf16 v[116:119], v[220:223], v[176:179], v[116:119]
	global_load_lds_dwordx4 v252, s[32:33]
	v_mfma_f32_16x16x32_bf16 v[124:127], v[220:223], v[188:191], v[124:127]
	s_add_u32 s30, s30, s4
	s_addc_u32 s31, s31, s5
	s_add_u32 s56, s56, s4
	s_addc_u32 s57, s57, s5
	v_mfma_f32_16x16x32_bf16 v[124:127], v[224:227], v[192:195], v[124:127]
	s_add_u32 s32, s32, s4
	s_addc_u32 s33, s33, s5
	s_add_u32 s58, s58, s4
	s_addc_u32 s59, s59, s5
	v_mfma_f32_16x16x32_bf16 v[120:123], v[216:219], v[192:195], v[120:123]
	v_mfma_f32_16x16x32_bf16 v[120:123], v[212:215], v[188:191], v[120:123]
	s_add_i32 s34, s34, -1
	s_cmp_lg_u32 s34, 1
	s_cbranch_scc1 .Lp1_nosw1
	s_add_u32 s45, s16, 1
	s_and_b32 s40, s45, 1
	s_lshl_b32 s4, s40, 8
	s_sub_u32 s4, 128, s4
	s_sub_u32 s5, 0, s40
	s_mul_i32 s8, s40, 3968
	s_add_u32 s30, s26, s8
	s_addc_u32 s31, s27, 0
	s_add_u32 s32, s28, s8
	s_addc_u32 s33, s29, 0
	s_add_u32 s56, s30, 0x80000
	s_addc_u32 s57, s31, 0
	s_add_u32 s58, s32, 0x80000
	s_addc_u32 s59, s33, 0

; __device__ __forceinline__ unsigned xb_ld(unsigned* p)              { return __hip_atomic_load(p, __ATOMIC_RELAXED, __HIP_MEMORY_SCOPE_AGENT); }
; __device__ __forceinline__ unsigned xb_add(unsigned* p, unsigned v) { return __hip_atomic_fetch_add(p, v, __ATOMIC_RELAXED, __HIP_MEMORY_SCOPE_AGENT); }
; #define XB_SPIN(cond, bar) do { unsigned _sp = 0; while (cond) { __builtin_amdgcn_s_sleep(1); \
;     if ((++_sp & 255u) == 0u) { if (xb_ld(&(bar)[XB_TMO])) break; if (_sp > XB_SPIN_CAP) { atomicAdd(&(bar)[XB_TMO], 1u); break; } } } } while (0)
; #define GRID_BAR(k) do { if (IN(k) && IN((k) + 1)) xcd_barrier(bar); } while (0)
; __device__ __forceinline__ void xcd_barrier(const XcdBarrier& b) {
;     asm volatile("s_waitcnt vmcnt(0)" ::: "memory");
;     __syncthreads();
;     if (threadIdx.x == 0) {
;         unsigned* bar = b.bar;
;         __builtin_amdgcn_s_waitcnt(0);
;         unsigned nloc = b.st[0], nx = b.st[1];
;         if (nloc == 0u) { xcd_barrier_complete(bar, b.x, nloc, nx); b.st[0] = nloc; b.st[1] = nx; }
;         const unsigned old = xb_add(&bar[XB_XSUB(b.x)], 1u);
;         const unsigned gen = old / nloc;
;         if (old + 1u == (gen + 1u) * nloc) {
;             __builtin_amdgcn_fence(__ATOMIC_RELEASE, "agent");
;             asm volatile("s_waitcnt vmcnt(0)" ::: "memory");
;             const unsigned og = xb_add(&bar[XB_TOP], 1u);
;             const unsigned tg = og / nx;
;             if (og + 1u == (tg + 1u) * nx) xb_add(&bar[XB_TOPGEN], 1u);
;             else XB_SPIN(xb_ld(&bar[XB_TOPGEN]) == tg, bar);
;             __builtin_amdgcn_fence(__ATOMIC_ACQUIRE, "agent");
;             xb_add(&bar[XB_XGEN(b.x)], 1u);
;             asm volatile("s_waitcnt vmcnt(0)" ::: "memory");
;         } else {
;             XB_SPIN(xb_ld(&bar[XB_XGEN(b.x)]) == gen, bar);
;             __builtin_amdgcn_fence(__ATOMIC_ACQUIRE, "agent");
;             asm volatile("s_waitcnt vmcnt(0)" ::: "memory");
;         }
;     }
;     __syncthreads();
; }
; __global__ void __launch_bounds__(NWAVES * 64, 2) hybrid_fwd(Args args) {
;     ...
;     GRID_BAR(1);
.LBB0_207:
	s_or_b64 exec, exec, s[4:5]
	s_waitcnt lgkmcnt(0)
	s_barrier
	v_mov_b32_e32 v254, 0x2d000
	global_load_dword v253, v254, s[76:77] sc1
	v_readlane_b32 s100, v244, 4
	s_waitcnt vmcnt(0)
	v_readfirstlane_b32 s99, v253
	s_cmp_eq_u32 s99, 0
	s_cselect_b32 s99, 1, 0
	s_cmp_eq_u32 s100, 0x100
	s_cselect_b32 s99, s99, 0

; __device__ __forceinline__ unsigned xb_ld(unsigned* p)              { return __hip_atomic_load(p, __ATOMIC_RELAXED, __HIP_MEMORY_SCOPE_AGENT); }
; __device__ __forceinline__ unsigned xb_add(unsigned* p, unsigned v) { return __hip_atomic_fetch_add(p, v, __ATOMIC_RELAXED, __HIP_MEMORY_SCOPE_AGENT); }
; #define XB_SPIN(cond, bar) do { unsigned _sp = 0; while (cond) { __builtin_amdgcn_s_sleep(1); \
;     if ((++_sp & 255u) == 0u) { if (xb_ld(&(bar)[XB_TMO])) break; if (_sp > XB_SPIN_CAP) { atomicAdd(&(bar)[XB_TMO], 1u); break; } } } } while (0)
; #define GRID_BAR(k) do { if (IN(k) && IN((k) + 1)) xcd_barrier(bar); } while (0)
; __device__ __forceinline__ void xcd_barrier(const XcdBarrier& b) {
;     asm volatile("s_waitcnt vmcnt(0)" ::: "memory");
;     __syncthreads();
;     if (threadIdx.x == 0) {
;         unsigned* bar = b.bar;
;         __builtin_amdgcn_s_waitcnt(0);
;         unsigned nloc = b.st[0], nx = b.st[1];
;         if (nloc == 0u) { xcd_barrier_complete(bar, b.x, nloc, nx); b.st[0] = nloc; b.st[1] = nx; }
;         const unsigned old = xb_add(&bar[XB_XSUB(b.x)], 1u);
;         const unsigned gen = old / nloc;
;         if (old + 1u == (gen + 1u) * nloc) {
;             __builtin_amdgcn_fence(__ATOMIC_RELEASE, "agent");
;             asm volatile("s_waitcnt vmcnt(0)" ::: "memory");
;             const unsigned og = xb_add(&bar[XB_TOP], 1u);
;             const unsigned tg = og / nx;
;             if (og + 1u == (tg + 1u) * nx) xb_add(&bar[XB_TOPGEN], 1u);
;             else XB_SPIN(xb_ld(&bar[XB_TOPGEN]) == tg, bar);
;             __builtin_amdgcn_fence(__ATOMIC_ACQUIRE, "agent");
;             xb_add(&bar[XB_XGEN(b.x)], 1u);
;             asm volatile("s_waitcnt vmcnt(0)" ::: "memory");
;         } else {
;             XB_SPIN(xb_ld(&bar[XB_XGEN(b.x)]) == gen, bar);
;             __builtin_amdgcn_fence(__ATOMIC_ACQUIRE, "agent");
;             asm volatile("s_waitcnt vmcnt(0)" ::: "memory");
;         }
;     }
;     __syncthreads();
; }
; __global__ void __launch_bounds__(NWAVES * 64, 2) hybrid_fwd(Args args) {
;     ...
;     GRID_BAR(3);
.LBB0_618:
	s_cmp_gt_i32 s71, 4
	s_cselect_b64 s[0:1], -1, 0
	s_and_b64 s[4:5], s[6:7], s[0:1]
	s_andn2_b64 vcc, exec, s[4:5]
	s_cbranch_vccnz .LBB0_672
	s_waitcnt vmcnt(0)
	s_waitcnt vmcnt(0)
	s_barrier
	s_and_saveexec_b64 s[4:5], s[96:97]
	s_cbranch_execz .LBB0_671
	s_cmp_eq_u32 s99, 1
	s_cbranch_scc0 .Lgb3_global
	s_and_b32 s100, s2, 7
	s_lshl_b32 s100, s100, 8
	s_add_u32 s100, s100, 0x2d800
	v_mov_b32_e32 v254, s100
	v_mov_b32_e32 v255, 1
	global_atomic_add v253, v254, v255, s[76:77] sc0
	s_waitcnt vmcnt(0)
	v_readfirstlane_b32 s100, v253
	s_lshr_b32 s98, s100, 5
	s_add_u32 s100, s100, 1
	s_and_b32 s100, s100, 31
	s_cmp_eq_u32 s100, 0
	s_cbranch_scc0 .Lgb3_spin
	global_atomic_add v254, v255, s[76:77] offset:2048
	s_branch .Lgb3_acq
.Lgb3_spin:
	s_mov_b32 s100, 0
.Lgb3_loop:
	global_load_dword v253, v254, s[76:77] offset:2048 sc1
	s_waitcnt vmcnt(0)
	v_readfirstlane_b32 s101, v253
	s_cmp_lg_u32 s101, s98
	s_cbranch_scc1 .Lgb3_acq
	s_sleep 1
	s_add_u32 s100, s100, 1
	s_cmp_lt_u32 s100, 0x40000
	s_cbranch_scc1 .Lgb3_loop
.Lgb3_acq:
	s_mov_b32 s101, 0
	buffer_inv sc1
	s_waitcnt vmcnt(0)
	s_branch .LBB0_671
.Lgb3_global:
	s_add_i32 s3, 0, 0x20fc0
	v_mov_b32_e32 v0, s3
	s_waitcnt vmcnt(0) expcnt(0) lgkmcnt(0)
	ds_read_b32 v2, v0
	s_add_i32 s3, 0, 0x20fc4
	v_mov_b32_e32 v0, s3
	ds_read_b32 v0, v0
	s_waitcnt lgkmcnt(1)
	v_cmp_ne_u32_e32 vcc, 0, v2
	s_cbranch_vccnz .LBB0_635
	v_readlane_b32 s6, v244, 4
	v_readlane_b32 s7, v244, 5
	v_readlane_b32 s3, v244, 6
	s_mul_i32 s3, s7, s3
	s_mul_i32 s3, s3, s6
	s_add_u32 s6, s76, 0x20200
	s_addc_u32 s7, s77, 0
	s_add_u32 s8, s76, 0x20400
	s_addc_u32 s9, s77, 0
	s_add_u32 s10, s76, 0x20500
	s_addc_u32 s11, s77, 0
	s_add_u32 s12, s76, 0x20600
	s_addc_u32 s13, s77, 0
	s_add_u32 s14, s76, 0x20700
	s_addc_u32 s15, s77, 0
	s_add_u32 s16, s76, 0x20800
	s_addc_u32 s17, s77, 0
	s_add_u32 s18, s76, 0x20900
	s_addc_u32 s19, s77, 0
	s_add_u32 s20, s76, 0x20a00
	s_addc_u32 s21, s77, 0
	s_add_u32 s22, s76, 0x20b00
	s_addc_u32 s23, s77, 0
	s_add_u32 s24, s76, 0x20c00
	s_addc_u32 s25, s77, 0
	s_add_u32 s26, s76, 0x20d00
	s_addc_u32 s27, s77, 0
	s_add_u32 s28, s76, 0x20e00
	s_addc_u32 s29, s77, 0
	s_add_u32 s30, s76, 0x20f00
	s_addc_u32 s31, s77, 0
	s_add_u32 s34, s76, 0x21000
	s_addc_u32 s35, s77, 0
	s_add_u32 s36, s76, 0x21100
	s_addc_u32 s37, s77, 0
	s_add_u32 s38, s76, 0x21200
	s_addc_u32 s39, s77, 0
	s_add_u32 s40, s76, 0x21300
	s_addc_u32 s41, s77, 0
	s_mov_b32 s33, 1
	v_mov_b32_e32 v16, 0
	s_branch .LBB0_623

; __device__ __forceinline__ unsigned xb_ld(unsigned* p)              { return __hip_atomic_load(p, __ATOMIC_RELAXED, __HIP_MEMORY_SCOPE_AGENT); }
; __device__ __forceinline__ unsigned xb_add(unsigned* p, unsigned v) { return __hip_atomic_fetch_add(p, v, __ATOMIC_RELAXED, __HIP_MEMORY_SCOPE_AGENT); }
; #define XB_SPIN(cond, bar) do { unsigned _sp = 0; while (cond) { __builtin_amdgcn_s_sleep(1); \
;     if ((++_sp & 255u) == 0u) { if (xb_ld(&(bar)[XB_TMO])) break; if (_sp > XB_SPIN_CAP) { atomicAdd(&(bar)[XB_TMO], 1u); break; } } } } while (0)
; #define GRID_BAR(k) do { if (IN(k) && IN((k) + 1)) xcd_barrier(bar); } while (0)
; __device__ __forceinline__ void xcd_barrier(const XcdBarrier& b) {
;     asm volatile("s_waitcnt vmcnt(0)" ::: "memory");
;     __syncthreads();
;     if (threadIdx.x == 0) {
;         unsigned* bar = b.bar;
;         __builtin_amdgcn_s_waitcnt(0);
;         unsigned nloc = b.st[0], nx = b.st[1];
;         if (nloc == 0u) { xcd_barrier_complete(bar, b.x, nloc, nx); b.st[0] = nloc; b.st[1] = nx; }
;         const unsigned old = xb_add(&bar[XB_XSUB(b.x)], 1u);
;         const unsigned gen = old / nloc;
;         if (old + 1u == (gen + 1u) * nloc) {
;             __builtin_amdgcn_fence(__ATOMIC_RELEASE, "agent");
;             asm volatile("s_waitcnt vmcnt(0)" ::: "memory");
;             const unsigned og = xb_add(&bar[XB_TOP], 1u);
;             const unsigned tg = og / nx;
;             if (og + 1u == (tg + 1u) * nx) xb_add(&bar[XB_TOPGEN], 1u);
;             else XB_SPIN(xb_ld(&bar[XB_TOPGEN]) == tg, bar);
;             __builtin_amdgcn_fence(__ATOMIC_ACQUIRE, "agent");
;             xb_add(&bar[XB_XGEN(b.x)], 1u);
;             asm volatile("s_waitcnt vmcnt(0)" ::: "memory");
;         } else {
;             XB_SPIN(xb_ld(&bar[XB_XGEN(b.x)]) == gen, bar);
;             __builtin_amdgcn_fence(__ATOMIC_ACQUIRE, "agent");
;             asm volatile("s_waitcnt vmcnt(0)" ::: "memory");
;         }
;     }
;     __syncthreads();
; }
; __global__ void __launch_bounds__(NWAVES * 64, 2) hybrid_fwd(Args args) {
;     ...
;     GRID_BAR(4);
.LBB0_715:
	s_cmp_gt_i32 s71, 5
	s_cselect_b64 s[0:1], -1, 0
	s_and_b64 s[4:5], s[6:7], s[0:1]
	s_andn2_b64 vcc, exec, s[4:5]
	s_cbranch_vccnz .LBB0_769
	s_waitcnt vmcnt(0)
	s_waitcnt vmcnt(0) lgkmcnt(0)
	s_barrier
	s_and_saveexec_b64 s[4:5], s[96:97]
	s_cbranch_execz .LBB0_768
	s_cmp_eq_u32 s99, 1
	s_cbranch_scc0 .Lgb4_global
	s_and_b32 s100, s2, 7
	s_lshl_b32 s100, s100, 8
	s_add_u32 s100, s100, 0x2d800
	v_mov_b32_e32 v254, s100
	v_mov_b32_e32 v255, 1
	global_atomic_add v253, v254, v255, s[76:77] sc0
	s_waitcnt vmcnt(0)
	v_readfirstlane_b32 s100, v253
	s_lshr_b32 s98, s100, 5
	s_add_u32 s100, s100, 1
	s_and_b32 s100, s100, 31
	s_cmp_eq_u32 s100, 0
	s_cbranch_scc0 .Lgb4_spin
	global_atomic_add v254, v255, s[76:77] offset:2048
	s_branch .Lgb4_acq

; __device__ __forceinline__ unsigned xb_ld(unsigned* p)              { return __hip_atomic_load(p, __ATOMIC_RELAXED, __HIP_MEMORY_SCOPE_AGENT); }
; __device__ __forceinline__ unsigned xb_add(unsigned* p, unsigned v) { return __hip_atomic_fetch_add(p, v, __ATOMIC_RELAXED, __HIP_MEMORY_SCOPE_AGENT); }
; #define XB_SPIN(cond, bar) do { unsigned _sp = 0; while (cond) { __builtin_amdgcn_s_sleep(1); \
;     if ((++_sp & 255u) == 0u) { if (xb_ld(&(bar)[XB_TMO])) break; if (_sp > XB_SPIN_CAP) { atomicAdd(&(bar)[XB_TMO], 1u); break; } } } } while (0)
; #define GRID_BAR(k) do { if (IN(k) && IN((k) + 1)) xcd_barrier(bar); } while (0)
; __device__ __forceinline__ void xcd_barrier(const XcdBarrier& b) {
;     asm volatile("s_waitcnt vmcnt(0)" ::: "memory");
;     __syncthreads();
;     if (threadIdx.x == 0) {
;         unsigned* bar = b.bar;
;         __builtin_amdgcn_s_waitcnt(0);
;         unsigned nloc = b.st[0], nx = b.st[1];
;         if (nloc == 0u) { xcd_barrier_complete(bar, b.x, nloc, nx); b.st[0] = nloc; b.st[1] = nx; }
;         const unsigned old = xb_add(&bar[XB_XSUB(b.x)], 1u);
;         const unsigned gen = old / nloc;
;         if (old + 1u == (gen + 1u) * nloc) {
;             __builtin_amdgcn_fence(__ATOMIC_RELEASE, "agent");
;             asm volatile("s_waitcnt vmcnt(0)" ::: "memory");
;             const unsigned og = xb_add(&bar[XB_TOP], 1u);
;             const unsigned tg = og / nx;
;             if (og + 1u == (tg + 1u) * nx) xb_add(&bar[XB_TOPGEN], 1u);
;             else XB_SPIN(xb_ld(&bar[XB_TOPGEN]) == tg, bar);
;             __builtin_amdgcn_fence(__ATOMIC_ACQUIRE, "agent");
;             xb_add(&bar[XB_XGEN(b.x)], 1u);
;             asm volatile("s_waitcnt vmcnt(0)" ::: "memory");
;         } else {
;             XB_SPIN(xb_ld(&bar[XB_XGEN(b.x)]) == gen, bar);
;             __builtin_amdgcn_fence(__ATOMIC_ACQUIRE, "agent");
;             asm volatile("s_waitcnt vmcnt(0)" ::: "memory");
;         }
;     }
;     __syncthreads();
; }
; __global__ void __launch_bounds__(NWAVES * 64, 2) hybrid_fwd(Args args) {
;     ...
;     GRID_BAR(5);
.LBB0_786:
	s_cmp_gt_i32 s71, 6
	s_cselect_b64 s[0:1], -1, 0
	s_and_b64 s[4:5], s[4:5], s[0:1]
	s_andn2_b64 vcc, exec, s[4:5]
	s_cbranch_vccnz .LBB0_840
	s_waitcnt vmcnt(0)
	s_waitcnt vmcnt(0) lgkmcnt(0)
	s_barrier
	s_and_saveexec_b64 s[4:5], s[96:97]
	s_cbranch_execz .LBB0_839
	s_cmp_eq_u32 s99, 1
	s_cbranch_scc0 .Lgb5_global
	s_and_b32 s100, s2, 7
	s_lshl_b32 s100, s100, 8
	s_add_u32 s100, s100, 0x2d800
	v_mov_b32_e32 v254, s100
	v_mov_b32_e32 v255, 1
	global_atomic_add v253, v254, v255, s[76:77] sc0
	s_waitcnt vmcnt(0)
	v_readfirstlane_b32 s100, v253
	s_lshr_b32 s98, s100, 5
	s_add_u32 s100, s100, 1
	s_and_b32 s100, s100, 31
	s_cmp_eq_u32 s100, 0
	s_cbranch_scc0 .Lgb5_spin
	global_atomic_add v254, v255, s[76:77] offset:2048
	s_branch .Lgb5_acq

; #define PG8_STAGE(bufoff, gbase, voff) do { _Pragma("unroll") for (int _i = 0; _i < 2; ++_i) \
;         __builtin_amdgcn_global_load_lds((const unsigned*)((const char*)(gbase) + (voff)[_i]), (PG8_LAS unsigned*)(lds + (bufoff) + ldsw + _i * 8192), 16, 0, 0); } while (0)
; #define PG8_LDA(dst, b, h) do { _Pragma("unroll") for (int m = 0; m < 4; ++m) _Pragma("unroll") for (int k = 0; k < 2; ++k) dst[m][k] = *(const PG8_LAS bf16x8*)(lds + PG8_SA(b, h) + aoff + m * 2048 + k * 1024); } while (0)
; #define PG8_LDB(dst, b, h) do { _Pragma("unroll") for (int n = 0; n < 2; ++n) _Pragma("unroll") for (int k = 0; k < 2; ++k) dst[n][k] = *(const PG8_LAS bf16x8*)(lds + PG8_SB(b, h) + boff + n * 2048 + k * 1024); } while (0)
; #define PG8_MMA(ai, bj, At, Bt) do { __builtin_amdgcn_s_setprio(1); _Pragma("unroll") for (int m = 0; m < 4; ++m) _Pragma("unroll") for (int n = 0; n < 2; ++n) _Pragma("unroll") for (int k = 0; k < 2; ++k) \
;         acc[ai][bj][m][n] = __builtin_amdgcn_mfma_f32_16x16x32_bf16(Bt[n][k], At[m][k], acc[ai][bj][m][n], 0, 0, 0); __builtin_amdgcn_s_setprio(0); } while (0)
; #define PG8_WAIT_V(n) asm volatile("s_waitcnt vmcnt(" #n ")" ::: "memory")
; template <class Epi, class Sched, bool ALIGN_EPI = false, bool SP2 = false>
; __device__ __forceinline__ void gemm_phase(PG8_LAS unsigned char* lds, const Gemm g, const Sched& S, const Epi& E) {
;     ...
;             PG8_LDB(B0, 0, 0); PG8_LDB(B1, 0, 1); PG8_SCHED; PG8_LDA(At, 0, 0); PG8_STAGE(PG8_SA(1, 1), a1 + hstep, voffA);
;             PG8_WAIT_V(8); PG8_WAIT_L(0); PG8_BAR; PG8_MMA(0, 0, At, B0); PG8_MMA(0, 1, At, B1); PG8_BAR; PG8_SCHED;
;             PG8_LDA(At, 0, 1); PG8_STAGE(PG8_SB(0, 0), b2, voffB); PG8_STAGE(PG8_SB(0, 1), b2 + hstep, voffB); PG8_STAGE(PG8_SA(0, 0), a2, voffA);
;             PG8_WAIT_V(8); PG8_WAIT_L(0); PG8_BAR; PG8_MMA(1, 0, At, B0); PG8_MMA(1, 1, At, B1); PG8_BAR; PG8_SCHED;
;             PG8_LDB(B0, 1, 0); PG8_LDB(B1, 1, 1); PG8_SCHED; PG8_LDA(At, 1, 0); PG8_STAGE(PG8_SA(0, 1), a2 + hstep, voffA);
;             PG8_WAIT_V(8); PG8_WAIT_L(0); PG8_BAR; PG8_MMA(0, 0, At, B0); PG8_MMA(0, 1, At, B1); PG8_BAR; PG8_SCHED;
;             PG8_LDA(At, 1, 1); PG8_STAGE(PG8_SB(1, 0), b3, voffB); PG8_STAGE(PG8_SB(1, 1), b3 + hstep, voffB); PG8_STAGE(PG8_SA(1, 0), a3, voffA);
;             PG8_WAIT_V(8); PG8_WAIT_L(0); PG8_BAR; PG8_MMA(1, 0, At, B0); PG8_MMA(1, 1, At, B1); PG8_BAR; PG8_SCHED;
.Lp6_kloop0:
	s_waitcnt vmcnt(8)
	s_waitcnt lgkmcnt(0)
	s_barrier
	v_mfma_f32_16x16x32_bf16 v[0:3], v[196:199], v[128:131], v[0:3]
	ds_read_b128 v[212:215], v247 offset:16384
	v_mfma_f32_16x16x32_bf16 v[0:3], v[200:203], v[132:135], v[0:3]
	ds_read_b128 v[216:219], v248 offset:16384
	v_mfma_f32_16x16x32_bf16 v[4:7], v[208:211], v[132:135], v[4:7]
	ds_read_b128 v[220:223], v247 offset:18432
	v_mfma_f32_16x16x32_bf16 v[4:7], v[204:207], v[128:131], v[4:7]
	ds_read_b128 v[224:227], v248 offset:18432
	v_mfma_f32_16x16x32_bf16 v[12:15], v[204:207], v[136:139], v[12:15]
	s_add_i32 m0, s35, 0x0
	v_mfma_f32_16x16x32_bf16 v[12:15], v[208:211], v[140:143], v[12:15]
	global_load_lds_dwordx4 v249, s[30:31]
	v_mfma_f32_16x16x32_bf16 v[8:11], v[200:203], v[140:143], v[8:11]
	s_add_i32 m0, s35, 0x2000
	v_mfma_f32_16x16x32_bf16 v[8:11], v[196:199], v[136:139], v[8:11]
	global_load_lds_dwordx4 v250, s[30:31]
	v_mfma_f32_16x16x32_bf16 v[16:19], v[196:199], v[144:147], v[16:19]
	s_add_i32 m0, s35, 0x10000
	v_mfma_f32_16x16x32_bf16 v[16:19], v[200:203], v[148:151], v[16:19]
	global_load_lds_dwordx4 v251, s[32:33]
	v_mfma_f32_16x16x32_bf16 v[20:23], v[208:211], v[148:151], v[20:23]
	s_add_i32 m0, s35, 0x12000
	v_mfma_f32_16x16x32_bf16 v[20:23], v[204:207], v[144:147], v[20:23]
	global_load_lds_dwordx4 v252, s[32:33]
	v_mfma_f32_16x16x32_bf16 v[28:31], v[204:207], v[152:155], v[28:31]
	ds_read_b128 v[160:163], v245 offset:16384
	v_mfma_f32_16x16x32_bf16 v[28:31], v[208:211], v[156:159], v[28:31]
	ds_read_b128 v[164:167], v246 offset:16384
	v_mfma_f32_16x16x32_bf16 v[24:27], v[200:203], v[156:159], v[24:27]
	ds_read_b128 v[168:171], v245 offset:18432
	v_mfma_f32_16x16x32_bf16 v[24:27], v[196:199], v[152:155], v[24:27]
	ds_read_b128 v[172:175], v246 offset:18432
	s_waitcnt lgkmcnt(4)
	v_mfma_f32_16x16x32_bf16 v[32:35], v[212:215], v[128:131], v[32:35]
	ds_read_b128 v[176:179], v245 offset:20480
	v_mfma_f32_16x16x32_bf16 v[32:35], v[216:219], v[132:135], v[32:35]
	ds_read_b128 v[180:183], v246 offset:20480
	v_mfma_f32_16x16x32_bf16 v[36:39], v[224:227], v[132:135], v[36:39]
	ds_read_b128 v[188:191], v245 offset:22528
	v_mfma_f32_16x16x32_bf16 v[36:39], v[220:223], v[128:131], v[36:39]
	ds_read_b128 v[192:195], v246 offset:22528
	v_mfma_f32_16x16x32_bf16 v[44:47], v[220:223], v[136:139], v[44:47]
	v_mfma_f32_16x16x32_bf16 v[44:47], v[224:227], v[140:143], v[44:47]
	v_mfma_f32_16x16x32_bf16 v[40:43], v[216:219], v[140:143], v[40:43]
	v_mfma_f32_16x16x32_bf16 v[40:43], v[212:215], v[136:139], v[40:43]
	v_mfma_f32_16x16x32_bf16 v[48:51], v[212:215], v[144:147], v[48:51]
	v_mfma_f32_16x16x32_bf16 v[48:51], v[216:219], v[148:151], v[48:51]
	v_mfma_f32_16x16x32_bf16 v[52:55], v[224:227], v[148:151], v[52:55]
	v_mfma_f32_16x16x32_bf16 v[52:55], v[220:223], v[144:147], v[52:55]
	v_mfma_f32_16x16x32_bf16 v[60:63], v[220:223], v[152:155], v[60:63]
	v_mfma_f32_16x16x32_bf16 v[60:63], v[224:227], v[156:159], v[60:63]
	v_mfma_f32_16x16x32_bf16 v[56:59], v[216:219], v[156:159], v[56:59]
	v_mfma_f32_16x16x32_bf16 v[56:59], v[212:215], v[152:155], v[56:59]
	s_waitcnt vmcnt(8)
	s_waitcnt lgkmcnt(0)
	s_barrier
	v_mfma_f32_16x16x32_bf16 v[96:99], v[212:215], v[160:163], v[96:99]
	s_add_i32 m0, s35, 0x4000
	v_mfma_f32_16x16x32_bf16 v[96:99], v[216:219], v[164:167], v[96:99]
	global_load_lds_dwordx4 v249, s[56:57]
	v_mfma_f32_16x16x32_bf16 v[100:103], v[224:227], v[164:167], v[100:103]
	s_add_i32 m0, s35, 0x6000
	v_mfma_f32_16x16x32_bf16 v[100:103], v[220:223], v[160:163], v[100:103]
	global_load_lds_dwordx4 v250, s[56:57]
	v_mfma_f32_16x16x32_bf16 v[108:111], v[220:223], v[168:171], v[108:111]
	s_add_i32 m0, s35, 0x14000
	v_mfma_f32_16x16x32_bf16 v[108:111], v[224:227], v[172:175], v[108:111]
	global_load_lds_dwordx4 v251, s[58:59]
	v_mfma_f32_16x16x32_bf16 v[104:107], v[216:219], v[172:175], v[104:107]
	s_add_i32 m0, s35, 0x16000
	v_mfma_f32_16x16x32_bf16 v[104:107], v[212:215], v[168:171], v[104:107]
	global_load_lds_dwordx4 v252, s[58:59]
	v_mfma_f32_16x16x32_bf16 v[112:115], v[212:215], v[176:179], v[112:115]
	ds_read_b128 v[128:131], v245 offset:32768
	v_mfma_f32_16x16x32_bf16 v[112:115], v[216:219], v[180:183], v[112:115]
	ds_read_b128 v[132:135], v246 offset:32768
	v_mfma_f32_16x16x32_bf16 v[116:119], v[224:227], v[180:183], v[116:119]
	ds_read_b128 v[136:139], v245 offset:34816
	v_mfma_f32_16x16x32_bf16 v[116:119], v[220:223], v[176:179], v[116:119]
	ds_read_b128 v[140:143], v246 offset:34816
	v_mfma_f32_16x16x32_bf16 v[124:127], v[220:223], v[188:191], v[124:127]
	ds_read_b128 v[144:147], v245 offset:36864
	v_mfma_f32_16x16x32_bf16 v[124:127], v[224:227], v[192:195], v[124:127]
	ds_read_b128 v[148:151], v246 offset:36864
	v_mfma_f32_16x16x32_bf16 v[120:123], v[216:219], v[192:195], v[120:123]
	ds_read_b128 v[152:155], v245 offset:38912
	v_mfma_f32_16x16x32_bf16 v[120:123], v[212:215], v[188:191], v[120:123]
	ds_read_b128 v[156:159], v246 offset:38912
	v_mfma_f32_16x16x32_bf16 v[64:67], v[196:199], v[160:163], v[64:67]
	ds_read_b128 v[212:215], v247 offset:49152
	v_mfma_f32_16x16x32_bf16 v[64:67], v[200:203], v[164:167], v[64:67]
	ds_read_b128 v[216:219], v248 offset:49152
	v_mfma_f32_16x16x32_bf16 v[68:71], v[208:211], v[164:167], v[68:71]
	ds_read_b128 v[220:223], v247 offset:51200
	v_mfma_f32_16x16x32_bf16 v[68:71], v[204:207], v[160:163], v[68:71]
	ds_read_b128 v[224:227], v248 offset:51200
	v_mfma_f32_16x16x32_bf16 v[76:79], v[204:207], v[168:171], v[76:79]
	s_add_u32 s30, s30, s4
	s_addc_u32 s31, s31, s5
	s_add_u32 s56, s56, s4
	s_addc_u32 s57, s57, s5
	v_mfma_f32_16x16x32_bf16 v[76:79], v[208:211], v[172:175], v[76:79]
	s_add_u32 s32, s32, s4
	s_addc_u32 s33, s33, s5
	s_add_u32 s58, s58, s4
	s_addc_u32 s59, s59, s5
	v_mfma_f32_16x16x32_bf16 v[72:75], v[200:203], v[172:175], v[72:75]
	v_mfma_f32_16x16x32_bf16 v[72:75], v[196:199], v[168:171], v[72:75]
	v_mfma_f32_16x16x32_bf16 v[80:83], v[196:199], v[176:179], v[80:83]
	v_mfma_f32_16x16x32_bf16 v[80:83], v[200:203], v[180:183], v[80:83]
	v_mfma_f32_16x16x32_bf16 v[84:87], v[208:211], v[180:183], v[84:87]
	v_mfma_f32_16x16x32_bf16 v[84:87], v[204:207], v[176:179], v[84:87]
	v_mfma_f32_16x16x32_bf16 v[92:95], v[204:207], v[188:191], v[92:95]
	v_mfma_f32_16x16x32_bf16 v[92:95], v[208:211], v[192:195], v[92:95]
	v_mfma_f32_16x16x32_bf16 v[88:91], v[200:203], v[192:195], v[88:91]
	v_mfma_f32_16x16x32_bf16 v[88:91], v[196:199], v[188:191], v[88:91]
	s_waitcnt vmcnt(8)
	s_waitcnt lgkmcnt(0)
	s_barrier
; #define PG8_STAGE(bufoff, gbase, voff) do { _Pragma("unroll") for (int _i = 0; _i < 2; ++_i) \
;         __builtin_amdgcn_global_load_lds((const unsigned*)((const char*)(gbase) + (voff)[_i]), (PG8_LAS unsigned*)(lds + (bufoff) + ldsw + _i * 8192), 16, 0, 0); } while (0)
; #define PG8_LDA(dst, b, h) do { _Pragma("unroll") for (int m = 0; m < 4; ++m) _Pragma("unroll") for (int k = 0; k < 2; ++k) dst[m][k] = *(const PG8_LAS bf16x8*)(lds + PG8_SA(b, h) + aoff + m * 2048 + k * 1024); } while (0)
; #define PG8_LDB(dst, b, h) do { _Pragma("unroll") for (int n = 0; n < 2; ++n) _Pragma("unroll") for (int k = 0; k < 2; ++k) dst[n][k] = *(const PG8_LAS bf16x8*)(lds + PG8_SB(b, h) + boff + n * 2048 + k * 1024); } while (0)
; #define PG8_MMA(ai, bj, At, Bt) do { __builtin_amdgcn_s_setprio(1); _Pragma("unroll") for (int m = 0; m < 4; ++m) _Pragma("unroll") for (int n = 0; n < 2; ++n) _Pragma("unroll") for (int k = 0; k < 2; ++k) \
;         acc[ai][bj][m][n] = __builtin_amdgcn_mfma_f32_16x16x32_bf16(Bt[n][k], At[m][k], acc[ai][bj][m][n], 0, 0, 0); __builtin_amdgcn_s_setprio(0); } while (0)
; #define PG8_WAIT_V(n) asm volatile("s_waitcnt vmcnt(" #n ")" ::: "memory")
; template <class Epi, class Sched, bool ALIGN_EPI = false, bool SP2 = false>
; __device__ __forceinline__ void gemm_phase(PG8_LAS unsigned char* lds, const Gemm g, const Sched& S, const Epi& E) {
;     ...
;             PG8_LDB(B0, 0, 0); PG8_LDB(B1, 0, 1); PG8_SCHED; PG8_LDA(At, 0, 0); PG8_STAGE(PG8_SA(1, 1), a1 + hstep, voffA);
;             PG8_WAIT_V(8); PG8_WAIT_L(0); PG8_BAR; PG8_MMA(0, 0, At, B0); PG8_MMA(0, 1, At, B1); PG8_BAR; PG8_SCHED;
;             PG8_LDA(At, 0, 1); PG8_STAGE(PG8_SB(0, 0), b2, voffB); PG8_STAGE(PG8_SB(0, 1), b2 + hstep, voffB); PG8_STAGE(PG8_SA(0, 0), a2, voffA);
;             PG8_WAIT_V(8); PG8_WAIT_L(0); PG8_BAR; PG8_MMA(1, 0, At, B0); PG8_MMA(1, 1, At, B1); PG8_BAR; PG8_SCHED;
;             PG8_LDB(B0, 1, 0); PG8_LDB(B1, 1, 1); PG8_SCHED; PG8_LDA(At, 1, 0); PG8_STAGE(PG8_SA(0, 1), a2 + hstep, voffA);
;             PG8_WAIT_V(8); PG8_WAIT_L(0); PG8_BAR; PG8_MMA(0, 0, At, B0); PG8_MMA(0, 1, At, B1); PG8_BAR; PG8_SCHED;
;             PG8_LDA(At, 1, 1); PG8_STAGE(PG8_SB(1, 0), b3, voffB); PG8_STAGE(PG8_SB(1, 1), b3 + hstep, voffB); PG8_STAGE(PG8_SA(1, 0), a3, voffA);
;             PG8_WAIT_V(8); PG8_WAIT_L(0); PG8_BAR; PG8_MMA(1, 0, At, B0); PG8_MMA(1, 1, At, B1); PG8_BAR; PG8_SCHED;
	v_mfma_f32_16x16x32_bf16 v[32:35], v[212:215], v[128:131], v[32:35]
	ds_read_b128 v[196:199], v247 offset:32768
	v_mfma_f32_16x16x32_bf16 v[32:35], v[216:219], v[132:135], v[32:35]
	ds_read_b128 v[200:203], v248 offset:32768
	v_mfma_f32_16x16x32_bf16 v[36:39], v[224:227], v[132:135], v[36:39]
	ds_read_b128 v[204:207], v247 offset:34816
	v_mfma_f32_16x16x32_bf16 v[36:39], v[220:223], v[128:131], v[36:39]
	ds_read_b128 v[208:211], v248 offset:34816
	v_mfma_f32_16x16x32_bf16 v[44:47], v[220:223], v[136:139], v[44:47]
	s_add_i32 m0, s35, 0x8000
	v_mfma_f32_16x16x32_bf16 v[44:47], v[224:227], v[140:143], v[44:47]
	global_load_lds_dwordx4 v249, s[30:31]
	v_mfma_f32_16x16x32_bf16 v[40:43], v[216:219], v[140:143], v[40:43]
	s_add_i32 m0, s35, 0xa000
	v_mfma_f32_16x16x32_bf16 v[40:43], v[212:215], v[136:139], v[40:43]
	global_load_lds_dwordx4 v250, s[30:31]
	v_mfma_f32_16x16x32_bf16 v[48:51], v[212:215], v[144:147], v[48:51]
	s_add_i32 m0, s35, 0x1c000
	v_mfma_f32_16x16x32_bf16 v[48:51], v[216:219], v[148:151], v[48:51]
	global_load_lds_dwordx4 v251, s[58:59]
	v_mfma_f32_16x16x32_bf16 v[52:55], v[224:227], v[148:151], v[52:55]
	s_add_i32 m0, s35, 0x1e000
	v_mfma_f32_16x16x32_bf16 v[52:55], v[220:223], v[144:147], v[52:55]
	global_load_lds_dwordx4 v252, s[58:59]
	v_mfma_f32_16x16x32_bf16 v[60:63], v[220:223], v[152:155], v[60:63]
	ds_read_b128 v[160:163], v245 offset:49152
	v_mfma_f32_16x16x32_bf16 v[60:63], v[224:227], v[156:159], v[60:63]
	ds_read_b128 v[164:167], v246 offset:49152
	v_mfma_f32_16x16x32_bf16 v[56:59], v[216:219], v[156:159], v[56:59]
	ds_read_b128 v[168:171], v245 offset:51200
	v_mfma_f32_16x16x32_bf16 v[56:59], v[212:215], v[152:155], v[56:59]
	ds_read_b128 v[172:175], v246 offset:51200
	s_waitcnt lgkmcnt(4)
	v_mfma_f32_16x16x32_bf16 v[0:3], v[196:199], v[128:131], v[0:3]
	ds_read_b128 v[176:179], v245 offset:53248
	v_mfma_f32_16x16x32_bf16 v[0:3], v[200:203], v[132:135], v[0:3]
	ds_read_b128 v[180:183], v246 offset:53248
	v_mfma_f32_16x16x32_bf16 v[4:7], v[208:211], v[132:135], v[4:7]
	ds_read_b128 v[188:191], v245 offset:55296
	v_mfma_f32_16x16x32_bf16 v[4:7], v[204:207], v[128:131], v[4:7]
	ds_read_b128 v[192:195], v246 offset:55296
	v_mfma_f32_16x16x32_bf16 v[12:15], v[204:207], v[136:139], v[12:15]
	v_mfma_f32_16x16x32_bf16 v[12:15], v[208:211], v[140:143], v[12:15]
	v_mfma_f32_16x16x32_bf16 v[8:11], v[200:203], v[140:143], v[8:11]
	v_mfma_f32_16x16x32_bf16 v[8:11], v[196:199], v[136:139], v[8:11]
	v_mfma_f32_16x16x32_bf16 v[16:19], v[196:199], v[144:147], v[16:19]
	v_mfma_f32_16x16x32_bf16 v[16:19], v[200:203], v[148:151], v[16:19]
	v_mfma_f32_16x16x32_bf16 v[20:23], v[208:211], v[148:151], v[20:23]
	v_mfma_f32_16x16x32_bf16 v[20:23], v[204:207], v[144:147], v[20:23]
	v_mfma_f32_16x16x32_bf16 v[28:31], v[204:207], v[152:155], v[28:31]
	v_mfma_f32_16x16x32_bf16 v[28:31], v[208:211], v[156:159], v[28:31]
	v_mfma_f32_16x16x32_bf16 v[24:27], v[200:203], v[156:159], v[24:27]
	v_mfma_f32_16x16x32_bf16 v[24:27], v[196:199], v[152:155], v[24:27]
	s_waitcnt vmcnt(8)
	s_waitcnt lgkmcnt(0)
	s_barrier
	v_mfma_f32_16x16x32_bf16 v[64:67], v[196:199], v[160:163], v[64:67]
	s_add_i32 m0, s35, 0xc000
	v_mfma_f32_16x16x32_bf16 v[64:67], v[200:203], v[164:167], v[64:67]
	global_load_lds_dwordx4 v249, s[56:57]
	v_mfma_f32_16x16x32_bf16 v[68:71], v[208:211], v[164:167], v[68:71]
	s_add_i32 m0, s35, 0xe000
	v_mfma_f32_16x16x32_bf16 v[68:71], v[204:207], v[160:163], v[68:71]
	global_load_lds_dwordx4 v250, s[56:57]
	v_mfma_f32_16x16x32_bf16 v[76:79], v[204:207], v[168:171], v[76:79]
	s_add_i32 m0, s35, 0x18000
	v_mfma_f32_16x16x32_bf16 v[76:79], v[208:211], v[172:175], v[76:79]
	global_load_lds_dwordx4 v251, s[32:33]
	v_mfma_f32_16x16x32_bf16 v[72:75], v[200:203], v[172:175], v[72:75]
	s_add_i32 m0, s35, 0x1a000
	v_mfma_f32_16x16x32_bf16 v[72:75], v[196:199], v[168:171], v[72:75]
	global_load_lds_dwordx4 v252, s[32:33]
	v_mfma_f32_16x16x32_bf16 v[80:83], v[196:199], v[176:179], v[80:83]
	ds_read_b128 v[128:131], v245 offset:0
	v_mfma_f32_16x16x32_bf16 v[80:83], v[200:203], v[180:183], v[80:83]
	ds_read_b128 v[132:135], v246 offset:0
	v_mfma_f32_16x16x32_bf16 v[84:87], v[208:211], v[180:183], v[84:87]
	ds_read_b128 v[136:139], v245 offset:2048
	v_mfma_f32_16x16x32_bf16 v[84:87], v[204:207], v[176:179], v[84:87]
	ds_read_b128 v[140:143], v246 offset:2048
	v_mfma_f32_16x16x32_bf16 v[92:95], v[204:207], v[188:191], v[92:95]
	ds_read_b128 v[144:147], v245 offset:4096
	v_mfma_f32_16x16x32_bf16 v[92:95], v[208:211], v[192:195], v[92:95]
	ds_read_b128 v[148:151], v246 offset:4096
	v_mfma_f32_16x16x32_bf16 v[88:91], v[200:203], v[192:195], v[88:91]
	ds_read_b128 v[152:155], v245 offset:6144
	v_mfma_f32_16x16x32_bf16 v[88:91], v[196:199], v[188:191], v[88:91]
	ds_read_b128 v[156:159], v246 offset:6144
	v_mfma_f32_16x16x32_bf16 v[96:99], v[212:215], v[160:163], v[96:99]
	ds_read_b128 v[196:199], v247 offset:0
	v_mfma_f32_16x16x32_bf16 v[96:99], v[216:219], v[164:167], v[96:99]
	ds_read_b128 v[200:203], v248 offset:0
	v_mfma_f32_16x16x32_bf16 v[100:103], v[224:227], v[164:167], v[100:103]
	ds_read_b128 v[204:207], v247 offset:2048
	v_mfma_f32_16x16x32_bf16 v[100:103], v[220:223], v[160:163], v[100:103]
	ds_read_b128 v[208:211], v248 offset:2048
	v_mfma_f32_16x16x32_bf16 v[108:111], v[220:223], v[168:171], v[108:111]
	s_add_u32 s30, s30, s4
	s_addc_u32 s31, s31, s5
	s_add_u32 s56, s56, s4
	s_addc_u32 s57, s57, s5
	v_mfma_f32_16x16x32_bf16 v[108:111], v[224:227], v[172:175], v[108:111]
	s_add_u32 s32, s32, s4
	s_addc_u32 s33, s33, s5
	s_add_u32 s58, s58, s4
	s_addc_u32 s59, s59, s5
	v_mfma_f32_16x16x32_bf16 v[104:107], v[216:219], v[172:175], v[104:107]
	v_mfma_f32_16x16x32_bf16 v[104:107], v[212:215], v[168:171], v[104:107]
	v_mfma_f32_16x16x32_bf16 v[112:115], v[212:215], v[176:179], v[112:115]
	v_mfma_f32_16x16x32_bf16 v[112:115], v[216:219], v[180:183], v[112:115]
	v_mfma_f32_16x16x32_bf16 v[116:119], v[224:227], v[180:183], v[116:119]
	v_mfma_f32_16x16x32_bf16 v[116:119], v[220:223], v[176:179], v[116:119]
	v_mfma_f32_16x16x32_bf16 v[124:127], v[220:223], v[188:191], v[124:127]
	v_mfma_f32_16x16x32_bf16 v[124:127], v[224:227], v[192:195], v[124:127]
	v_mfma_f32_16x16x32_bf16 v[120:123], v[216:219], v[192:195], v[120:123]
	v_mfma_f32_16x16x32_bf16 v[120:123], v[212:215], v[188:191], v[120:123]
	s_add_i32 s34, s34, -1
	s_cmp_lg_u32 s34, 1
	s_cbranch_scc1 .Lp6_nosw0
	s_add_u32 s45, s16, 1
	s_and_b32 s40, s45, 1
	s_lshl_b32 s4, s40, 8
	s_sub_u32 s4, 128, s4
	s_sub_u32 s5, 0, s40
	s_mul_i32 s8, s40, 11136
	s_add_u32 s30, s26, s8
	s_addc_u32 s31, s27, 0
	s_add_u32 s32, s28, s8
	s_addc_u32 s33, s29, 0
	s_add_u32 s56, s30, 0x160000
	s_addc_u32 s57, s31, 0
	s_add_u32 s58, s32, 0x160000
	s_addc_u32 s59, s33, 0

; #define PG8_STAGE(bufoff, gbase, voff) do { _Pragma("unroll") for (int _i = 0; _i < 2; ++_i) \
;         __builtin_amdgcn_global_load_lds((const unsigned*)((const char*)(gbase) + (voff)[_i]), (PG8_LAS unsigned*)(lds + (bufoff) + ldsw + _i * 8192), 16, 0, 0); } while (0)
; #define PG8_LDA(dst, b, h) do { _Pragma("unroll") for (int m = 0; m < 4; ++m) _Pragma("unroll") for (int k = 0; k < 2; ++k) dst[m][k] = *(const PG8_LAS bf16x8*)(lds + PG8_SA(b, h) + aoff + m * 2048 + k * 1024); } while (0)
; #define PG8_LDB(dst, b, h) do { _Pragma("unroll") for (int n = 0; n < 2; ++n) _Pragma("unroll") for (int k = 0; k < 2; ++k) dst[n][k] = *(const PG8_LAS bf16x8*)(lds + PG8_SB(b, h) + boff + n * 2048 + k * 1024); } while (0)
; #define PG8_MMA(ai, bj, At, Bt) do { __builtin_amdgcn_s_setprio(1); _Pragma("unroll") for (int m = 0; m < 4; ++m) _Pragma("unroll") for (int n = 0; n < 2; ++n) _Pragma("unroll") for (int k = 0; k < 2; ++k) \
;         acc[ai][bj][m][n] = __builtin_amdgcn_mfma_f32_16x16x32_bf16(Bt[n][k], At[m][k], acc[ai][bj][m][n], 0, 0, 0); __builtin_amdgcn_s_setprio(0); } while (0)
; #define PG8_WAIT_V(n) asm volatile("s_waitcnt vmcnt(" #n ")" ::: "memory")
; template <class Epi, class Sched, bool ALIGN_EPI = false, bool SP2 = false>
; __device__ __forceinline__ void gemm_phase(PG8_LAS unsigned char* lds, const Gemm g, const Sched& S, const Epi& E) {
;     ...
;             PG8_LDB(B0, 0, 0); PG8_LDB(B1, 0, 1); PG8_SCHED; PG8_LDA(At, 0, 0); PG8_STAGE(PG8_SA(1, 1), a1 + hstep, voffA);
;             PG8_WAIT_V(8); PG8_WAIT_L(0); PG8_BAR; PG8_MMA(0, 0, At, B0); PG8_MMA(0, 1, At, B1); PG8_BAR; PG8_SCHED;
;             PG8_LDA(At, 0, 1); PG8_STAGE(PG8_SB(0, 0), b2, voffB); PG8_STAGE(PG8_SB(0, 1), b2 + hstep, voffB); PG8_STAGE(PG8_SA(0, 0), a2, voffA);
;             PG8_WAIT_V(8); PG8_WAIT_L(0); PG8_BAR; PG8_MMA(1, 0, At, B0); PG8_MMA(1, 1, At, B1); PG8_BAR; PG8_SCHED;
;             PG8_LDB(B0, 1, 0); PG8_LDB(B1, 1, 1); PG8_SCHED; PG8_LDA(At, 1, 0); PG8_STAGE(PG8_SA(0, 1), a2 + hstep, voffA);
;             PG8_WAIT_V(8); PG8_WAIT_L(0); PG8_BAR; PG8_MMA(0, 0, At, B0); PG8_MMA(0, 1, At, B1); PG8_BAR; PG8_SCHED;
;             PG8_LDA(At, 1, 1); PG8_STAGE(PG8_SB(1, 0), b3, voffB); PG8_STAGE(PG8_SB(1, 1), b3 + hstep, voffB); PG8_STAGE(PG8_SA(1, 0), a3, voffA);
;             PG8_WAIT_V(8); PG8_WAIT_L(0); PG8_BAR; PG8_MMA(1, 0, At, B0); PG8_MMA(1, 1, At, B1); PG8_BAR; PG8_SCHED;
.Lp6_kloop1:
	s_waitcnt vmcnt(8)
	s_waitcnt lgkmcnt(0)
	s_barrier
	v_mfma_f32_16x16x32_bf16 v[0:3], v[196:199], v[128:131], v[0:3]
	ds_read_b128 v[212:215], v247 offset:16384
	v_mfma_f32_16x16x32_bf16 v[0:3], v[200:203], v[132:135], v[0:3]
	ds_read_b128 v[216:219], v248 offset:16384
	v_mfma_f32_16x16x32_bf16 v[4:7], v[208:211], v[132:135], v[4:7]
	ds_read_b128 v[220:223], v247 offset:18432
	v_mfma_f32_16x16x32_bf16 v[4:7], v[204:207], v[128:131], v[4:7]
	ds_read_b128 v[224:227], v248 offset:18432
	v_mfma_f32_16x16x32_bf16 v[12:15], v[204:207], v[136:139], v[12:15]
	ds_read_b128 v[160:163], v245 offset:16384
	v_mfma_f32_16x16x32_bf16 v[12:15], v[208:211], v[140:143], v[12:15]
	ds_read_b128 v[164:167], v246 offset:16384
	v_mfma_f32_16x16x32_bf16 v[8:11], v[200:203], v[140:143], v[8:11]
	ds_read_b128 v[168:171], v245 offset:18432
	v_mfma_f32_16x16x32_bf16 v[8:11], v[196:199], v[136:139], v[8:11]
	ds_read_b128 v[172:175], v246 offset:18432
	v_mfma_f32_16x16x32_bf16 v[16:19], v[196:199], v[144:147], v[16:19]
	ds_read_b128 v[176:179], v245 offset:20480
	v_mfma_f32_16x16x32_bf16 v[16:19], v[200:203], v[148:151], v[16:19]
	ds_read_b128 v[180:183], v246 offset:20480
	v_mfma_f32_16x16x32_bf16 v[20:23], v[208:211], v[148:151], v[20:23]
	ds_read_b128 v[188:191], v245 offset:22528
	v_mfma_f32_16x16x32_bf16 v[20:23], v[204:207], v[144:147], v[20:23]
	ds_read_b128 v[192:195], v246 offset:22528
	v_mfma_f32_16x16x32_bf16 v[28:31], v[204:207], v[152:155], v[28:31]
	v_mfma_f32_16x16x32_bf16 v[28:31], v[208:211], v[156:159], v[28:31]
	v_mfma_f32_16x16x32_bf16 v[24:27], v[200:203], v[156:159], v[24:27]
	v_mfma_f32_16x16x32_bf16 v[24:27], v[196:199], v[152:155], v[24:27]
	s_waitcnt lgkmcnt(8)
	v_mfma_f32_16x16x32_bf16 v[32:35], v[212:215], v[128:131], v[32:35]
	v_mfma_f32_16x16x32_bf16 v[32:35], v[216:219], v[132:135], v[32:35]
	s_add_i32 m0, s35, 0x0
	v_mfma_f32_16x16x32_bf16 v[36:39], v[224:227], v[132:135], v[36:39]
	global_load_lds_dwordx4 v249, s[30:31]
	v_mfma_f32_16x16x32_bf16 v[36:39], v[220:223], v[128:131], v[36:39]
	v_mfma_f32_16x16x32_bf16 v[44:47], v[220:223], v[136:139], v[44:47]
	s_add_i32 m0, s35, 0x2000
	v_mfma_f32_16x16x32_bf16 v[44:47], v[224:227], v[140:143], v[44:47]
	global_load_lds_dwordx4 v250, s[30:31]
	v_mfma_f32_16x16x32_bf16 v[40:43], v[216:219], v[140:143], v[40:43]
	v_mfma_f32_16x16x32_bf16 v[40:43], v[212:215], v[136:139], v[40:43]
	s_add_i32 m0, s35, 0x10000
	v_mfma_f32_16x16x32_bf16 v[48:51], v[212:215], v[144:147], v[48:51]
	global_load_lds_dwordx4 v251, s[32:33]
	v_mfma_f32_16x16x32_bf16 v[48:51], v[216:219], v[148:151], v[48:51]
	v_mfma_f32_16x16x32_bf16 v[52:55], v[224:227], v[148:151], v[52:55]
	s_add_i32 m0, s35, 0x12000
	v_mfma_f32_16x16x32_bf16 v[52:55], v[220:223], v[144:147], v[52:55]
	global_load_lds_dwordx4 v252, s[32:33]
	v_mfma_f32_16x16x32_bf16 v[60:63], v[220:223], v[152:155], v[60:63]
	v_mfma_f32_16x16x32_bf16 v[60:63], v[224:227], v[156:159], v[60:63]
	v_mfma_f32_16x16x32_bf16 v[56:59], v[216:219], v[156:159], v[56:59]
	v_mfma_f32_16x16x32_bf16 v[56:59], v[212:215], v[152:155], v[56:59]
	s_waitcnt vmcnt(8)
	s_waitcnt lgkmcnt(0)
	s_barrier
	v_mfma_f32_16x16x32_bf16 v[96:99], v[212:215], v[160:163], v[96:99]
	ds_read_b128 v[128:131], v245 offset:32768
	v_mfma_f32_16x16x32_bf16 v[96:99], v[216:219], v[164:167], v[96:99]
	ds_read_b128 v[132:135], v246 offset:32768
	v_mfma_f32_16x16x32_bf16 v[100:103], v[224:227], v[164:167], v[100:103]
	ds_read_b128 v[136:139], v245 offset:34816
	v_mfma_f32_16x16x32_bf16 v[100:103], v[220:223], v[160:163], v[100:103]
	ds_read_b128 v[140:143], v246 offset:34816
	v_mfma_f32_16x16x32_bf16 v[108:111], v[220:223], v[168:171], v[108:111]
	ds_read_b128 v[144:147], v245 offset:36864
	v_mfma_f32_16x16x32_bf16 v[108:111], v[224:227], v[172:175], v[108:111]
	ds_read_b128 v[148:151], v246 offset:36864
	v_mfma_f32_16x16x32_bf16 v[104:107], v[216:219], v[172:175], v[104:107]
	ds_read_b128 v[152:155], v245 offset:38912
	v_mfma_f32_16x16x32_bf16 v[104:107], v[212:215], v[168:171], v[104:107]
	ds_read_b128 v[156:159], v246 offset:38912
	v_mfma_f32_16x16x32_bf16 v[112:115], v[212:215], v[176:179], v[112:115]
	v_mfma_f32_16x16x32_bf16 v[112:115], v[216:219], v[180:183], v[112:115]
	v_mfma_f32_16x16x32_bf16 v[116:119], v[224:227], v[180:183], v[116:119]
	v_mfma_f32_16x16x32_bf16 v[116:119], v[220:223], v[176:179], v[116:119]
	v_mfma_f32_16x16x32_bf16 v[124:127], v[220:223], v[188:191], v[124:127]
	v_mfma_f32_16x16x32_bf16 v[124:127], v[224:227], v[192:195], v[124:127]
	v_mfma_f32_16x16x32_bf16 v[120:123], v[216:219], v[192:195], v[120:123]
	v_mfma_f32_16x16x32_bf16 v[120:123], v[212:215], v[188:191], v[120:123]
	v_mfma_f32_16x16x32_bf16 v[64:67], v[196:199], v[160:163], v[64:67]
	ds_read_b128 v[212:215], v247 offset:49152
	v_mfma_f32_16x16x32_bf16 v[64:67], v[200:203], v[164:167], v[64:67]
	ds_read_b128 v[216:219], v248 offset:49152
	v_mfma_f32_16x16x32_bf16 v[68:71], v[208:211], v[164:167], v[68:71]
	ds_read_b128 v[220:223], v247 offset:51200
	v_mfma_f32_16x16x32_bf16 v[68:71], v[204:207], v[160:163], v[68:71]
	ds_read_b128 v[224:227], v248 offset:51200
	v_mfma_f32_16x16x32_bf16 v[76:79], v[204:207], v[168:171], v[76:79]
	s_add_i32 m0, s35, 0x4000
	v_mfma_f32_16x16x32_bf16 v[76:79], v[208:211], v[172:175], v[76:79]
	global_load_lds_dwordx4 v249, s[56:57]
	v_mfma_f32_16x16x32_bf16 v[72:75], v[200:203], v[172:175], v[72:75]
	s_add_i32 m0, s35, 0x6000
	v_mfma_f32_16x16x32_bf16 v[72:75], v[196:199], v[168:171], v[72:75]
	global_load_lds_dwordx4 v250, s[56:57]
	v_mfma_f32_16x16x32_bf16 v[80:83], v[196:199], v[176:179], v[80:83]
	s_add_i32 m0, s35, 0x14000
	v_mfma_f32_16x16x32_bf16 v[80:83], v[200:203], v[180:183], v[80:83]
	global_load_lds_dwordx4 v251, s[58:59]
	v_mfma_f32_16x16x32_bf16 v[84:87], v[208:211], v[180:183], v[84:87]
	s_add_i32 m0, s35, 0x16000
	v_mfma_f32_16x16x32_bf16 v[84:87], v[204:207], v[176:179], v[84:87]
	global_load_lds_dwordx4 v252, s[58:59]
	v_mfma_f32_16x16x32_bf16 v[92:95], v[204:207], v[188:191], v[92:95]
	s_add_u32 s30, s30, s4
	s_addc_u32 s31, s31, s5
	s_add_u32 s56, s56, s4
	s_addc_u32 s57, s57, s5
	v_mfma_f32_16x16x32_bf16 v[92:95], v[208:211], v[192:195], v[92:95]
	s_add_u32 s32, s32, s4
	s_addc_u32 s33, s33, s5
	s_add_u32 s58, s58, s4
	s_addc_u32 s59, s59, s5
	v_mfma_f32_16x16x32_bf16 v[88:91], v[200:203], v[192:195], v[88:91]
	v_mfma_f32_16x16x32_bf16 v[88:91], v[196:199], v[188:191], v[88:91]
	s_waitcnt vmcnt(8)
	s_waitcnt lgkmcnt(0)
	s_barrier
; #define PG8_STAGE(bufoff, gbase, voff) do { _Pragma("unroll") for (int _i = 0; _i < 2; ++_i) \
;         __builtin_amdgcn_global_load_lds((const unsigned*)((const char*)(gbase) + (voff)[_i]), (PG8_LAS unsigned*)(lds + (bufoff) + ldsw + _i * 8192), 16, 0, 0); } while (0)
; #define PG8_LDA(dst, b, h) do { _Pragma("unroll") for (int m = 0; m < 4; ++m) _Pragma("unroll") for (int k = 0; k < 2; ++k) dst[m][k] = *(const PG8_LAS bf16x8*)(lds + PG8_SA(b, h) + aoff + m * 2048 + k * 1024); } while (0)
; #define PG8_LDB(dst, b, h) do { _Pragma("unroll") for (int n = 0; n < 2; ++n) _Pragma("unroll") for (int k = 0; k < 2; ++k) dst[n][k] = *(const PG8_LAS bf16x8*)(lds + PG8_SB(b, h) + boff + n * 2048 + k * 1024); } while (0)
; #define PG8_MMA(ai, bj, At, Bt) do { __builtin_amdgcn_s_setprio(1); _Pragma("unroll") for (int m = 0; m < 4; ++m) _Pragma("unroll") for (int n = 0; n < 2; ++n) _Pragma("unroll") for (int k = 0; k < 2; ++k) \
;         acc[ai][bj][m][n] = __builtin_amdgcn_mfma_f32_16x16x32_bf16(Bt[n][k], At[m][k], acc[ai][bj][m][n], 0, 0, 0); __builtin_amdgcn_s_setprio(0); } while (0)
; template <class Epi, class Sched, bool ALIGN_EPI = false, bool SP2 = false>
; __device__ __forceinline__ void gemm_phase(PG8_LAS unsigned char* lds, const Gemm g, const Sched& S, const Epi& E) {
;     ...
;         const bool has_next = S.next(ui + 1, nxt);
;         const char* nA = has_next ? (const char*)g.A + (size_t)nxt.pm * tstep : cA; const char* nB = has_next ? (const char*)g.Bt + (size_t)nxt.pn * tstep : cB;
;         for (int t = 0; t < nt; t += 2) {
;             const bool last = (t == nt - 2);
;             const char* a1 = cA + (size_t)(t + 1) * kstep;
;             const char* a2 = last ? nA : cA + (size_t)(t + 2) * kstep; const char* b2 = last ? nB : cB + (size_t)(t + 2) * kstep;
;             const char* a3 = a2 + kstep; const char* b3 = b2 + kstep;
;     ...
;             PG8_LDB(B0, 1, 0); PG8_LDB(B1, 1, 1); PG8_SCHED; PG8_LDA(At, 1, 0); PG8_STAGE(PG8_SA(0, 1), a2 + hstep, voffA);
;             PG8_WAIT_V(8); PG8_WAIT_L(0); PG8_BAR; PG8_MMA(0, 0, At, B0); PG8_MMA(0, 1, At, B1); PG8_BAR; PG8_SCHED;
;             PG8_LDA(At, 1, 1); PG8_STAGE(PG8_SB(1, 0), b3, voffB); PG8_STAGE(PG8_SB(1, 1), b3 + hstep, voffB); PG8_STAGE(PG8_SA(1, 0), a3, voffA);
;             PG8_WAIT_V(8); PG8_WAIT_L(0); PG8_BAR; PG8_MMA(1, 0, At, B0); PG8_MMA(1, 1, At, B1); PG8_BAR; PG8_SCHED;
	v_mfma_f32_16x16x32_bf16 v[32:35], v[212:215], v[128:131], v[32:35]
	ds_read_b128 v[196:199], v247 offset:32768
	v_mfma_f32_16x16x32_bf16 v[32:35], v[216:219], v[132:135], v[32:35]
	ds_read_b128 v[200:203], v248 offset:32768
	v_mfma_f32_16x16x32_bf16 v[36:39], v[224:227], v[132:135], v[36:39]
	ds_read_b128 v[204:207], v247 offset:34816
	v_mfma_f32_16x16x32_bf16 v[36:39], v[220:223], v[128:131], v[36:39]
	ds_read_b128 v[208:211], v248 offset:34816
	v_mfma_f32_16x16x32_bf16 v[44:47], v[220:223], v[136:139], v[44:47]
	ds_read_b128 v[160:163], v245 offset:49152
	v_mfma_f32_16x16x32_bf16 v[44:47], v[224:227], v[140:143], v[44:47]
	ds_read_b128 v[164:167], v246 offset:49152
	v_mfma_f32_16x16x32_bf16 v[40:43], v[216:219], v[140:143], v[40:43]
	ds_read_b128 v[168:171], v245 offset:51200
	v_mfma_f32_16x16x32_bf16 v[40:43], v[212:215], v[136:139], v[40:43]
	ds_read_b128 v[172:175], v246 offset:51200
	v_mfma_f32_16x16x32_bf16 v[48:51], v[212:215], v[144:147], v[48:51]
	ds_read_b128 v[176:179], v245 offset:53248
	v_mfma_f32_16x16x32_bf16 v[48:51], v[216:219], v[148:151], v[48:51]
	ds_read_b128 v[180:183], v246 offset:53248
	v_mfma_f32_16x16x32_bf16 v[52:55], v[224:227], v[148:151], v[52:55]
	ds_read_b128 v[188:191], v245 offset:55296
	v_mfma_f32_16x16x32_bf16 v[52:55], v[220:223], v[144:147], v[52:55]
	ds_read_b128 v[192:195], v246 offset:55296
	v_mfma_f32_16x16x32_bf16 v[60:63], v[220:223], v[152:155], v[60:63]
	v_mfma_f32_16x16x32_bf16 v[60:63], v[224:227], v[156:159], v[60:63]
	v_mfma_f32_16x16x32_bf16 v[56:59], v[216:219], v[156:159], v[56:59]
	v_mfma_f32_16x16x32_bf16 v[56:59], v[212:215], v[152:155], v[56:59]
	s_waitcnt lgkmcnt(8)
	v_mfma_f32_16x16x32_bf16 v[0:3], v[196:199], v[128:131], v[0:3]
	v_mfma_f32_16x16x32_bf16 v[0:3], v[200:203], v[132:135], v[0:3]
	s_add_i32 m0, s35, 0x8000
	v_mfma_f32_16x16x32_bf16 v[4:7], v[208:211], v[132:135], v[4:7]
	global_load_lds_dwordx4 v249, s[30:31]
	v_mfma_f32_16x16x32_bf16 v[4:7], v[204:207], v[128:131], v[4:7]
	v_mfma_f32_16x16x32_bf16 v[12:15], v[204:207], v[136:139], v[12:15]
	s_add_i32 m0, s35, 0xa000
	v_mfma_f32_16x16x32_bf16 v[12:15], v[208:211], v[140:143], v[12:15]
	global_load_lds_dwordx4 v250, s[30:31]
	v_mfma_f32_16x16x32_bf16 v[8:11], v[200:203], v[140:143], v[8:11]
	v_mfma_f32_16x16x32_bf16 v[8:11], v[196:199], v[136:139], v[8:11]
	s_add_i32 m0, s35, 0x1c000
	v_mfma_f32_16x16x32_bf16 v[16:19], v[196:199], v[144:147], v[16:19]
	global_load_lds_dwordx4 v251, s[58:59]
	v_mfma_f32_16x16x32_bf16 v[16:19], v[200:203], v[148:151], v[16:19]
	v_mfma_f32_16x16x32_bf16 v[20:23], v[208:211], v[148:151], v[20:23]
	s_add_i32 m0, s35, 0x1e000
	v_mfma_f32_16x16x32_bf16 v[20:23], v[204:207], v[144:147], v[20:23]
	global_load_lds_dwordx4 v252, s[58:59]
	v_mfma_f32_16x16x32_bf16 v[28:31], v[204:207], v[152:155], v[28:31]
	v_mfma_f32_16x16x32_bf16 v[28:31], v[208:211], v[156:159], v[28:31]
	v_mfma_f32_16x16x32_bf16 v[24:27], v[200:203], v[156:159], v[24:27]
	v_mfma_f32_16x16x32_bf16 v[24:27], v[196:199], v[152:155], v[24:27]
	s_waitcnt vmcnt(8)
	s_waitcnt lgkmcnt(0)
	s_barrier
	v_mfma_f32_16x16x32_bf16 v[64:67], v[196:199], v[160:163], v[64:67]
	ds_read_b128 v[128:131], v245 offset:0
	v_mfma_f32_16x16x32_bf16 v[64:67], v[200:203], v[164:167], v[64:67]
	ds_read_b128 v[132:135], v246 offset:0
	v_mfma_f32_16x16x32_bf16 v[68:71], v[208:211], v[164:167], v[68:71]
	ds_read_b128 v[136:139], v245 offset:2048
	v_mfma_f32_16x16x32_bf16 v[68:71], v[204:207], v[160:163], v[68:71]
	ds_read_b128 v[140:143], v246 offset:2048
	v_mfma_f32_16x16x32_bf16 v[76:79], v[204:207], v[168:171], v[76:79]
	ds_read_b128 v[144:147], v245 offset:4096
	v_mfma_f32_16x16x32_bf16 v[76:79], v[208:211], v[172:175], v[76:79]
	ds_read_b128 v[148:151], v246 offset:4096
	v_mfma_f32_16x16x32_bf16 v[72:75], v[200:203], v[172:175], v[72:75]
	ds_read_b128 v[152:155], v245 offset:6144
	v_mfma_f32_16x16x32_bf16 v[72:75], v[196:199], v[168:171], v[72:75]
	ds_read_b128 v[156:159], v246 offset:6144
	v_mfma_f32_16x16x32_bf16 v[80:83], v[196:199], v[176:179], v[80:83]
	v_mfma_f32_16x16x32_bf16 v[80:83], v[200:203], v[180:183], v[80:83]
	v_mfma_f32_16x16x32_bf16 v[84:87], v[208:211], v[180:183], v[84:87]
	v_mfma_f32_16x16x32_bf16 v[84:87], v[204:207], v[176:179], v[84:87]
	v_mfma_f32_16x16x32_bf16 v[92:95], v[204:207], v[188:191], v[92:95]
	v_mfma_f32_16x16x32_bf16 v[92:95], v[208:211], v[192:195], v[92:95]
	v_mfma_f32_16x16x32_bf16 v[88:91], v[200:203], v[192:195], v[88:91]
	v_mfma_f32_16x16x32_bf16 v[88:91], v[196:199], v[188:191], v[88:91]
	v_mfma_f32_16x16x32_bf16 v[96:99], v[212:215], v[160:163], v[96:99]
	ds_read_b128 v[196:199], v247 offset:0
	v_mfma_f32_16x16x32_bf16 v[96:99], v[216:219], v[164:167], v[96:99]
	ds_read_b128 v[200:203], v248 offset:0
	v_mfma_f32_16x16x32_bf16 v[100:103], v[224:227], v[164:167], v[100:103]
	ds_read_b128 v[204:207], v247 offset:2048
	v_mfma_f32_16x16x32_bf16 v[100:103], v[220:223], v[160:163], v[100:103]
	ds_read_b128 v[208:211], v248 offset:2048
	v_mfma_f32_16x16x32_bf16 v[108:111], v[220:223], v[168:171], v[108:111]
	s_add_i32 m0, s35, 0xc000
	v_mfma_f32_16x16x32_bf16 v[108:111], v[224:227], v[172:175], v[108:111]
	global_load_lds_dwordx4 v249, s[56:57]
	v_mfma_f32_16x16x32_bf16 v[104:107], v[216:219], v[172:175], v[104:107]
	s_add_i32 m0, s35, 0xe000
	v_mfma_f32_16x16x32_bf16 v[104:107], v[212:215], v[168:171], v[104:107]
	global_load_lds_dwordx4 v250, s[56:57]
	v_mfma_f32_16x16x32_bf16 v[112:115], v[212:215], v[176:179], v[112:115]
	s_add_i32 m0, s35, 0x18000
	v_mfma_f32_16x16x32_bf16 v[112:115], v[216:219], v[180:183], v[112:115]
	global_load_lds_dwordx4 v251, s[32:33]
	v_mfma_f32_16x16x32_bf16 v[116:119], v[224:227], v[180:183], v[116:119]
	s_add_i32 m0, s35, 0x1a000
	v_mfma_f32_16x16x32_bf16 v[116:119], v[220:223], v[176:179], v[116:119]
	global_load_lds_dwordx4 v252, s[32:33]
	v_mfma_f32_16x16x32_bf16 v[124:127], v[220:223], v[188:191], v[124:127]
	s_add_u32 s30, s30, s4
	s_addc_u32 s31, s31, s5
	s_add_u32 s56, s56, s4
	s_addc_u32 s57, s57, s5
	v_mfma_f32_16x16x32_bf16 v[124:127], v[224:227], v[192:195], v[124:127]
	s_add_u32 s32, s32, s4
	s_addc_u32 s33, s33, s5
	s_add_u32 s58, s58, s4
	s_addc_u32 s59, s59, s5
	v_mfma_f32_16x16x32_bf16 v[120:123], v[216:219], v[192:195], v[120:123]
	v_mfma_f32_16x16x32_bf16 v[120:123], v[212:215], v[188:191], v[120:123]
	s_add_i32 s34, s34, -1
	s_cmp_lg_u32 s34, 1
	s_cbranch_scc1 .Lp6_nosw1
	s_add_u32 s45, s16, 1
	s_and_b32 s40, s45, 1
	s_lshl_b32 s4, s40, 8
	s_sub_u32 s4, 128, s4
	s_sub_u32 s5, 0, s40
	s_mul_i32 s8, s40, 11136
	s_add_u32 s30, s26, s8
	s_addc_u32 s31, s27, 0
	s_add_u32 s32, s28, s8
	s_addc_u32 s33, s29, 0
	s_add_u32 s56, s30, 0x160000
	s_addc_u32 s57, s31, 0
	s_add_u32 s58, s32, 0x160000
	s_addc_u32 s59, s33, 0
